# G1B sigmoid rcp+Newton; G5 third round as 64 half-M (128-row) tiles on 64 blocks via ai=1-free main-loop copy + 8-iteration residual epilogue; step-8 wprep moved to XCDs 2-7
# speedup vs baseline: 1.0001x; 1.0001x over previous
; __global__ void __launch_bounds__(NTHR) mega(P p) {
;     ...
;       const int bid = blockIdx.x, nb = gridDim.x;
;       int wl = -1, wmode = 0, rank = bid, count = nb, mod = 1, lo = 0, width = 1, sub_lo = 0, sub_hi = 0;
;       if (!(ls2 & 1)) {
;         if (step == 0) { wl = l; wmode = (l == 0) ? 0 : 2; }
;         else if ((step == 1 || step == 3 || step == 6) && l < 3 && nb == 256) {
;           const int ntl = (step == 1) ? 68 * 29 : (step == 3) ? 68 * 9 : 4 * 68 * 8;
;           const int rem = ntl - ((ntl + 255) / 256 - 1) * 256;
;           const int pos = (bid & 7) * 32 + (bid >> 3);
;           if (pos >= rem) {
;             wl = l + 1; wmode = 3; rank = pos - rem; count = 256 - rem;
;             sub_lo = (step == 1) ? 0 : (step == 3) ? 1660 : 3000;
;             sub_hi = (step == 1) ? 1660 : (step == 3) ? 3000 : 4096;
;           }
;         }
;         else if (step == 7 && l < 3) {
;           wl = l + 1; wmode = (nb == 256) ? 1 : 4;
;           if (nb == 256) {
;             count = 128; mod = 5;
;             if ((bid & 7) >= 4) { rank = (bid >> 3) * 4 + (bid & 7) - 4; lo = 4; width = 1; }
;             else wl = -1;
;           }
;         } else if (step == 8 && l < 3 && nb == 256 && (bid & 7) != 0) {
;           wl = l + 1; wmode = 1; rank = (bid >> 3) * 7 + (bid & 7) - 1; count = 224; mod = 5; lo = 0; width = 4;
;         }
.LBB0_63:
	s_or_b64 exec, exec, s[30:31]
	s_lshl_b32 s24, s74, 3
	s_add_u32 s0, s72, 0x568a000
	v_writelane_b32 v251, s0, 27
	s_addc_u32 s0, s73, 0
	s_cmpk_eq_i32 s74, 0x100
	v_writelane_b32 v251, s0, 28
	s_cselect_b64 s[0:1], -1, 0
	v_writelane_b32 v251, s0, 29
	s_and_b32 s6, s26, 7
	s_mul_i32 s5, s75, s74
	v_writelane_b32 v251, s1, 30
	v_sub_co_u32_e64 v0, s[0:1], s6, 2
	s_xor_b64 s[0:1], s[0:1], -1
	s_nop 0
	v_writelane_b32 v251, s0, 31
	v_readfirstlane_b32 s7, v0
	s_mov_b64 s[8:9], s[60:61]
	v_writelane_b32 v251, s1, 32
	s_ashr_i32 s0, s26, 3
	s_mul_i32 s1, s0, 6
	s_add_i32 s1, s7, s1
	s_cmp_gt_u32 s6, 3
	v_writelane_b32 v251, s1, 33
	s_cselect_b64 s[2:3], -1, 0
	s_ashr_i32 s1, s26, 1
	s_and_b32 s1, s1, -4
	v_writelane_b32 v251, s2, 34
	s_add_i32 s1, s6, s1
	s_add_i32 s1, s1, -4
	v_writelane_b32 v251, s3, 35
	v_writelane_b32 v251, s1, 36
	s_lshl_b32 s1, s26, 5
	s_and_b32 s1, s1, 0xe0
	s_add_i32 s0, s1, s0
	v_writelane_b32 v251, s0, 37
	s_lshl_b32 s95, s74, 9
	s_mul_i32 s0, s5, s33
	v_writelane_b32 v251, s0, 38
	s_add_u32 s0, s72, 0x39862800
	s_addc_u32 s1, s73, 0
	v_writelane_b32 v251, s0, 39
	s_mov_b64 s[14:15], s[66:67]
	s_mov_b32 s90, 0xffff0000
	v_writelane_b32 v251, s1, 40
	s_add_u32 s0, s72, 0x39862a00
	s_addc_u32 s1, s73, 0
	v_writelane_b32 v251, s0, 41
	v_mov_b32_e32 v1, 0
	v_mov_b32_e32 v170, 0x358637bd
	v_writelane_b32 v251, s1, 42
	s_add_u32 s0, s72, 0x39862b00
	s_addc_u32 s1, s73, 0
	v_writelane_b32 v251, s0, 43
	s_mov_b32 s31, 0x20000
	s_brev_b32 s30, -2
	v_writelane_b32 v251, s1, 44
	s_add_u32 s0, s72, 0x39862c00
	s_addc_u32 s1, s73, 0
	v_writelane_b32 v251, s0, 45
	v_mov_b32_e32 v195, 1
	v_bfrev_b32_e32 v196, 0.5
	v_writelane_b32 v251, s1, 46
	s_add_u32 s0, s72, 0x39862d00
	s_addc_u32 s1, s73, 0
	v_writelane_b32 v251, s0, 47
	v_mov_b32_e32 v197, 0x1000
	v_mov_b32_e32 v198, 0x100
	v_writelane_b32 v251, s1, 48
	s_add_u32 s0, s72, 0x39862e00
	s_addc_u32 s1, s73, 0
	v_writelane_b32 v251, s0, 49
	v_mov_b32_e32 v199, 0x41b17218
	v_mov_b32_e32 v200, 0x1dc
	v_writelane_b32 v251, s1, 50
	s_add_u32 s0, s72, 0x39862f00
	s_addc_u32 s1, s73, 0
	v_writelane_b32 v251, s0, 51
	v_mov_b32_e32 v201, 0x2200
	v_mov_b32_e32 v202, 0x198000
	v_writelane_b32 v251, s1, 52
	s_add_u32 s0, s72, 0x39863000
	s_addc_u32 s1, s73, 0
	v_writelane_b32 v251, s0, 53
	v_mov_b32_e32 v203, 0x110000
	s_movk_i32 s88, 0x1000
	v_writelane_b32 v251, s1, 54
	s_add_u32 s0, s72, 0x39863100
	s_addc_u32 s1, s73, 0
	v_writelane_b32 v251, s0, 55
	s_movk_i32 s33, 0x7fff
	s_mov_b32 s27, 0x7060302
	v_writelane_b32 v251, s1, 56
	s_add_u32 s0, s72, 0x39863200
	s_addc_u32 s1, s73, 0
	v_writelane_b32 v251, s0, 57
	s_mov_b32 s94, 0xf149f2ca
	s_mov_b32 s77, 0
	v_writelane_b32 v251, s1, 58
	s_add_u32 s0, s72, 0x39863300
	s_addc_u32 s1, s73, 0
	v_writelane_b32 v251, s0, 59
	s_mov_b32 s21, 0
	s_mov_b64 s[22:23], 0x2000
	v_writelane_b32 v251, s1, 60
	s_add_u32 s0, s72, 0x39863400
	s_addc_u32 s1, s73, 0
	v_writelane_b32 v251, s0, 61
	s_mov_b32 s91, -1
	s_mov_b64 s[92:93], 0x6000
	v_writelane_b32 v251, s1, 62
	s_add_u32 s0, s72, 0x39863500
	s_addc_u32 s1, s73, 0
	v_writelane_b32 v251, s0, 63
	s_barrier
; #define LAS __attribute__((address_space(3)))
; DEVI unsigned xb_ld(unsigned* p) { return __hip_atomic_load(p, __ATOMIC_RELAXED, __HIP_MEMORY_SCOPE_AGENT); }
; DEVI void xcd_barrier_complete(unsigned* bar, unsigned x, unsigned& nloc, unsigned& nx) {
;   const unsigned G = gridDim.x * gridDim.y * gridDim.z;
;   unsigned sum, cnt, mine, sp = 0u;
;   for (;;) {
;     sum = 0u; cnt = 0u; mine = 0u;
; #pragma unroll
;     for (unsigned j = 0; j < 16; ++j) { const unsigned c = xb_ld(&bar[XB_XCNT(j)]); sum += c; cnt += (c > 0u) ? 1u : 0u; mine = (j == x) ? c : mine; }
;     if (sum == G) break;
;     __builtin_amdgcn_s_sleep(1);
;     if ((++sp & 255u) == 0u) { if (xb_ld(&bar[XB_TMO])) break; if (sp > XB_SPIN_CAP) { atomicAdd(&bar[XB_TMO], 1u); break; } }
;   }
;   nloc = mine > 0u ? mine : 1u; nx = cnt > 0u ? cnt : 1u;
; }
; __global__ void __launch_bounds__(NTHR) mega(P p) {
;     ...
;   unsigned* bar = (unsigned*)(p.ws + O_BAR);
;   if (threadIdx.x == 0) xb_words = make_uint4(0u, 0u, 0u, 0u);
;   if (blockIdx.x == 0) {
;     for (int i = threadIdx.x; i < 4096; i += NTHR) bar[i] = 0u;
;   }
;   __syncthreads();
;   if (PHM & 1) phase_mod_partial(p);
;   grid.sync();
;   XcdBarrier xb = xcd_barrier_post(bar, (volatile LAS unsigned*)&xb_words);
;   if (PHM & 1) phase_mod_reduce(p);
;   grid.sync();
;   for (int ls2 = 0; ls2 < 36 * 2; ++ls2) {
	s_nop 0
	v_writelane_b32 v250, s1, 0
	s_add_u32 s0, s72, 0x39863600
	s_addc_u32 s1, s73, 0
	v_writelane_b32 v250, s0, 1
	s_nop 1
	v_writelane_b32 v250, s1, 2
	s_add_u32 s0, s72, 0x39863700
	s_addc_u32 s1, s73, 0
	v_writelane_b32 v250, s0, 3
	s_nop 1
	v_writelane_b32 v250, s1, 4
	s_add_u32 s0, s72, 0x39863800
	s_addc_u32 s1, s73, 0
	v_writelane_b32 v250, s0, 5
	s_nop 1
	v_writelane_b32 v250, s1, 6
	s_add_u32 s0, s72, 0x39863900
	s_addc_u32 s1, s73, 0
	v_writelane_b32 v250, s0, 7
	s_cmp_eq_u32 s4, 15
	s_nop 0
	v_writelane_b32 v250, s1, 8
	s_cselect_b64 s[0:1], -1, 0
	v_writelane_b32 v250, s0, 9
	s_cmp_eq_u32 s4, 14
	s_nop 0
	v_writelane_b32 v250, s1, 10
	s_cselect_b64 s[0:1], -1, 0
	v_writelane_b32 v250, s0, 11
	s_cmp_eq_u32 s4, 13
	s_nop 0
	v_writelane_b32 v250, s1, 12
	s_cselect_b64 s[0:1], -1, 0
	v_writelane_b32 v250, s0, 13
	s_cmp_eq_u32 s4, 12
	s_nop 0
	v_writelane_b32 v250, s1, 14
	s_cselect_b64 s[0:1], -1, 0
	v_writelane_b32 v250, s0, 15
	s_cmp_eq_u32 s4, 11
	s_nop 0
	v_writelane_b32 v250, s1, 16
	s_cselect_b64 s[0:1], -1, 0
	v_writelane_b32 v250, s0, 17
	s_cmp_eq_u32 s4, 10
	s_nop 0
	v_writelane_b32 v250, s1, 18
	s_cselect_b64 s[0:1], -1, 0
	v_writelane_b32 v250, s0, 19
	s_cmp_eq_u32 s4, 9
	s_nop 0
	v_writelane_b32 v250, s1, 20
	s_cselect_b64 s[0:1], -1, 0
	v_writelane_b32 v250, s0, 21
	s_cmp_eq_u32 s4, 8
	s_nop 0
	v_writelane_b32 v250, s1, 22
	s_cselect_b64 s[0:1], -1, 0
	v_writelane_b32 v250, s0, 23
	s_cmp_eq_u32 s4, 7
	s_nop 0
	v_writelane_b32 v250, s1, 24
	s_cselect_b64 s[0:1], -1, 0
	v_writelane_b32 v250, s0, 25
	s_cmp_eq_u32 s4, 6
	s_nop 0
	v_writelane_b32 v250, s1, 26
	s_cselect_b64 s[0:1], -1, 0
	v_writelane_b32 v250, s0, 27
	s_cmp_eq_u32 s4, 5
	s_nop 0
	v_writelane_b32 v250, s1, 28
	s_cselect_b64 s[0:1], -1, 0
	v_writelane_b32 v250, s0, 29
	s_cmp_eq_u32 s4, 4
	s_nop 0
	v_writelane_b32 v250, s1, 30
	s_cselect_b64 s[0:1], -1, 0
	v_writelane_b32 v250, s0, 31
	s_cmp_eq_u32 s4, 3
	s_nop 0
	v_writelane_b32 v250, s1, 32
	s_cselect_b64 s[0:1], -1, 0
	v_writelane_b32 v250, s0, 33
	s_cmp_eq_u32 s4, 2
	s_nop 0
	v_writelane_b32 v250, s1, 34
	s_cselect_b64 s[0:1], -1, 0
	v_writelane_b32 v250, s0, 35
	s_cmp_eq_u32 s4, 1
	s_nop 0
	v_writelane_b32 v250, s1, 36
	s_cselect_b64 s[0:1], -1, 0
	v_writelane_b32 v250, s0, 37
	s_cmp_eq_u32 s4, 0
	s_nop 0
	v_writelane_b32 v250, s1, 38
	s_cselect_b64 s[0:1], -1, 0
	v_writelane_b32 v250, s0, 39
	s_nop 1
	v_writelane_b32 v250, s1, 40
	s_lshl_b32 s0, s4, 8
	s_add_u32 s0, s50, s0
	s_addc_u32 s1, s51, 0
	s_add_u32 s2, s0, 0x1400
	s_addc_u32 s3, s1, 0
	v_writelane_b32 v250, s2, 41
	s_add_u32 s0, s0, 0x2400
	s_addc_u32 s1, s1, 0
	v_writelane_b32 v250, s3, 42
	v_writelane_b32 v250, s0, 43
	s_mov_b64 s[4:5], s[56:57]
	s_nop 0
	v_writelane_b32 v250, s1, 44
	s_mov_b32 s0, 0xe000
	v_add_u32_e64 v194, s0, 16
	s_add_u32 s0, s72, 0x39865a00
	s_addc_u32 s1, s73, 0
	v_writelane_b32 v250, s0, 45
	s_nop 1
	v_writelane_b32 v250, s1, 46
	s_add_u32 s0, s72, 0x39865b00
	s_addc_u32 s1, s73, 0
	v_writelane_b32 v250, s0, 47
	s_nop 1
	v_writelane_b32 v250, s1, 48
	s_add_u32 s0, s72, 0x5e8a800
	s_addc_u32 s1, s73, 0
	v_writelane_b32 v250, s0, 49
	s_ashr_i32 s25, s24, 31
	s_nop 0
	v_writelane_b32 v250, s1, 50
	s_lshl_b32 s0, s74, 4
	v_writelane_b32 v250, s0, 51
	s_lshl_b64 s[0:1], s[24:25], 12
	v_writelane_b32 v250, s0, 52
	s_nop 1
	v_writelane_b32 v250, s1, 53
	s_add_u32 s0, s72, 0x2210a000
	s_addc_u32 s1, s73, 0
	v_writelane_b32 v250, s0, 54
	s_nop 1
	v_writelane_b32 v250, s1, 55
	s_lshl_b64 s[0:1], s[24:25], 6
	v_writelane_b32 v250, s0, 56
	s_nop 1
	v_writelane_b32 v250, s1, 57
	s_lshl_b64 s[0:1], s[24:25], 11
	v_writelane_b32 v250, s0, 58
	s_nop 1
	v_writelane_b32 v250, s1, 59
	s_add_u32 s0, s72, 0x1ee0a000
	s_addc_u32 s1, s73, 0
	v_writelane_b32 v250, s0, 60
	s_nop 1
	v_writelane_b32 v250, s1, 61
	s_lshl_b64 s[0:1], s[24:25], 10
	v_writelane_b32 v250, s0, 62
	s_nop 1
	v_writelane_b32 v250, s1, 63
	s_add_u32 s0, s72, 0xa28c000
	s_addc_u32 s1, s73, 0
	v_writelane_b32 v249, s0, 0
	s_nop 1
	v_writelane_b32 v249, s1, 1
	s_mul_i32 s0, s74, 0x1d000
	s_mul_hi_i32 s1, s24, 0x3a00
	v_writelane_b32 v249, s0, 2
	s_nop 1
	v_writelane_b32 v249, s1, 3
	s_add_u32 s0, s72, 0xa28a000
	s_addc_u32 s1, s73, 0
	v_writelane_b32 v249, s0, 4
	s_nop 1
	v_writelane_b32 v249, s1, 5
	s_add_u32 s0, s72, 0xa28d480
	s_addc_u32 s1, s73, 0
	v_writelane_b32 v249, s0, 6
	s_nop 1
	v_writelane_b32 v249, s1, 7
	s_add_u32 s0, s72, 0x2663c000
	v_writelane_b32 v249, s0, 8
	s_addc_u32 s0, s73, 0
	v_writelane_b32 v249, s0, 9
	s_add_u32 s0, s72, 0x4e10000
	v_writelane_b32 v249, s0, 10
	s_addc_u32 s0, s73, 0
	v_writelane_b32 v249, s0, 11
	s_add_u32 s0, s72, 0x1b296000
	s_addc_u32 s1, s73, 0
	v_writelane_b32 v249, s0, 12
	s_nop 1
	v_writelane_b32 v249, s1, 13
	s_add_u32 s0, s72, 0x1cc0a100
	s_addc_u32 s1, s73, 0
	v_writelane_b32 v249, s0, 14
	s_nop 1
	v_writelane_b32 v249, s1, 15
	s_add_u32 s0, s72, 0x1b2ae000
	s_addc_u32 s1, s73, 0
	v_writelane_b32 v249, s0, 16
	s_nop 1
	v_writelane_b32 v249, s1, 17
	s_add_u32 s0, s72, 0x1cc0a300
	s_addc_u32 s1, s73, 0
	v_writelane_b32 v249, s0, 18
	s_nop 1
	v_writelane_b32 v249, s1, 19
	s_add_i32 s0, 16, 0x10000
	v_writelane_b32 v249, s0, 20
	s_add_i32 s0, 16, 0x14000
	v_writelane_b32 v249, s0, 21
	s_add_i32 s0, 16, 0x18000
	v_writelane_b32 v249, s0, 22
	s_add_i32 s0, 16, 0x1c000
	v_writelane_b32 v249, s0, 23
	s_add_i32 s0, 16, 0xda40
	v_writelane_b32 v249, s0, 24
	s_add_i32 s0, 16, 0x8c00
	v_writelane_b32 v249, s0, 25
	s_mov_b64 s[0:1], s[52:53]
	v_writelane_b32 v249, s0, 26
	s_nop 1
	v_writelane_b32 v249, s1, 27
	v_writelane_b32 v249, s2, 28
	v_writelane_b32 v249, s3, 29
	v_writelane_b32 v249, s4, 30
	v_writelane_b32 v249, s5, 31
	v_writelane_b32 v249, s6, 32
	v_writelane_b32 v249, s7, 33
	v_writelane_b32 v249, s8, 34
	v_writelane_b32 v249, s9, 35
	v_writelane_b32 v249, s10, 36
	v_writelane_b32 v249, s11, 37
	v_writelane_b32 v249, s12, 38
	v_writelane_b32 v249, s13, 39
	v_writelane_b32 v249, s14, 40
	v_writelane_b32 v249, s15, 41
	v_writelane_b32 v249, s68, 42
	s_nop 1
	v_writelane_b32 v249, s69, 43
	v_writelane_b32 v249, s70, 44
	v_writelane_b32 v249, s71, 45
	v_writelane_b32 v249, s72, 46
	v_writelane_b32 v249, s73, 47
	v_writelane_b32 v249, s74, 48
	v_writelane_b32 v249, s75, 49
	v_writelane_b32 v249, s84, 50
	s_nop 1
	v_writelane_b32 v249, s85, 51
	v_writelane_b32 v249, s95, 52
	v_writelane_b32 v249, s24, 53
	s_nop 1
	v_writelane_b32 v249, s25, 54
	s_branch .LBB0_67

; DEVI int xcd_remap(int t, int bid, int nblk) {
;   if (nblk != 256) return t;
;   int r = t / 256;
;   return r * 256 + (bid & 7) * 32 + (bid >> 3);
; }
; __device__ void gemm_step(const P& p, int step, int l) {
;     ...
;   for (int t0 = BIDX; t0 < (ntiles + 255) / 256 * 256; t0 += gridDim.x) {
;     const int t = xcd_remap(t0, BIDX, gridDim.x);
;     if (t >= ntiles) continue;
.LBB0_164:
	s_mov_b32 s98, 0
	v_readlane_b32 s2, v249, 57
	v_readlane_b32 s3, v249, 58
	s_and_b64 vcc, exec, s[2:3]
	s_mov_b32 s8, s74
	s_cbranch_vccnz .LBB0_166
	s_ashr_i32 s2, s74, 31
	s_lshr_b32 s2, s2, 24
	s_add_i32 s2, s74, s2
	s_and_b32 s2, s2, 0xffffff00
	s_add_i32 s8, s96, s2
	s_cmp_eq_u32 s86, 0x220
	s_cbranch_scc0 .Lhm_nomap
	s_cmp_eq_u32 s2, 0x200
	s_cbranch_scc0 .Lhm_nomap
	s_cmp_lt_u32 s96, 64
	s_cbranch_scc0 .LBB0_163
	s_lshr_b32 s8, s96, 1
	s_addk_i32 s8, 0x200
	s_and_b32 s98, s96, 1
	s_add_i32 s98, s98, 1
.Lhm_nomap:
.LBB0_166:
	s_cmp_ge_i32 s8, s86
	s_cbranch_scc1 .LBB0_163
	s_and_b64 vcc, exec, s[40:41]
	s_cbranch_vccnz .LBB0_172
	v_readlane_b32 s4, v249, 56
	s_mov_b64 s[2:3], -1
	s_mov_b64 s[56:57], 0
	s_cmp_lt_i32 s4, 6
	s_mov_b64 s[54:55], 0
	s_cbranch_scc1 .LBB0_173
	s_mul_hi_i32 s2, s8, 0x78787879
	s_lshr_b32 s3, s2, 31
	s_ashr_i32 s2, s2, 8
	s_add_i32 s36, s2, s3
	s_ashr_i32 s37, s36, 31
	s_lshl_b64 s[2:3], s[36:37], 21
	v_readlane_b32 s4, v248, 3
	s_add_u32 s28, s4, s2
	v_readlane_b32 s2, v248, 5
	s_addc_u32 s29, s2, s3
	s_lshl_b32 s2, s36, 9
	s_ashr_i32 s3, s2, 31
	s_lshl_b64 s[2:3], s[2:3], 1
	v_readlane_b32 s4, v248, 2
	s_add_u32 s44, s4, s2
	v_readlane_b32 s2, v249, 56
	s_addc_u32 s45, s75, s3
	s_and_b32 s4, 0xffff, s2
	s_cmp_gt_i32 s4, 6
	s_mov_b64 s[2:3], 0
	s_cbranch_scc0 .LBB0_178
	s_cmp_eq_u32 s4, 7
	s_mov_b64 s[34:35], 0
	s_cbranch_scc0 .LBB0_316
	s_ashr_i32 s4, s8, 31
	s_lshr_b32 s4, s4, 25
	s_add_i32 s4, s8, s4
	s_ashr_i32 s5, s4, 7
	s_and_b32 s4, s4, 0xffffff80
	s_sub_i32 s6, s8, s4
	s_lshl_b32 s4, s5, 2
	s_and_b32 s5, s6, 3
	s_or_b32 s4, s5, s4
	s_ashr_i32 s6, s6, 2
	s_mov_b64 s[46:47], 0
	s_movk_i32 s5, 0x800
	s_mov_b64 s[36:37], -1
	s_mov_b32 s71, 5
	s_mov_b32 s7, 64
	s_branch .LBB0_317

; #define WAIT_V(n) asm volatile("s_waitcnt vmcnt(" #n ")" ::: "memory")
; #define BAR __builtin_amdgcn_s_barrier()
; DEVI void gemm256(const P& p, const u16* A, int lda, const u16* Bt, int ldb, int K, int brow, int bcol, int mode,
;                         int aux, int layer, int bmode) {
;     ...
;   int wid = TIDX >> 6, lane = TIDX & 63, wr = wid >> 2, wc = wid & 3, fr = lane & 15, fq = lane >> 4;
;     ...
;   f32x4 acc[2][2][4][2] = {};
;   bf16x8 At[4][2], B0[2][2], B1[2][2];
;     ...
;   f32x4 acc[2][1][4][2] = {};
;   bf16x8 At[4][2], B0[2][2];
;     ...
;   int nt = K / BK;
;   const int bhalf = bmode ? 4096 : HALF;
;   int offA0, offA1, offB0, offB1;
;   __amdgpu_buffer_rsrc_t rsA = __builtin_amdgcn_make_buffer_rsrc((void*)A, 0, 0x7fffffff, 0x00020000);
;   __amdgpu_buffer_rsrc_t rsB = __builtin_amdgcn_make_buffer_rsrc((void*)Bt, 0, 0x7fffffff, 0x00020000);
;   {
;     int r0, c0, r1, c1;
;     stage_rc(TIDX * 16, r0, c0);
;     stage_rc(TIDX * 16 + 8192, r1, c1);
;     offA0 = (r0 * lda + c0) * 2; offA1 = (r1 * lda + c1) * 2;
;     offB0 = (r0 * ldb + c0) * 2; offB1 = bmode ? offB0 + 2048 * ldb * 2 : (r1 * ldb + c1) * 2;
;   }
;     ...
;   STAGEB(SB(0, 0), bcol, 0);
;   STAGEA(SA(0, 0), brow, 0);
;   STAGEB(SB(0, 1), bcol + bhalf, 0);
;   STAGEA(SA(0, 1), brow + HALF, 0);
;   if (wr == 1) BAR;
;   WAIT_V(4);
;   BAR;
;   STAGEB(SB(1, 0), bcol, 1);
;   STAGEA(SA(1, 0), brow, 1);
;   STAGEB(SB(1, 1), bcol + bhalf, 1);
;   WAIT_V(6);
;   BAR;
.LBB0_189:
	s_lshl_b32 s70, s4, 8
	s_cmp_eq_u32 s98, 2
	s_cselect_b32 s99, 0x80, 0
	s_add_i32 s70, s70, s99
	s_mul_i32 s97, s7, s6
	s_and_b64 s[2:3], s[46:47], exec
	s_movk_i32 s2, 0x80
	s_mul_i32 s3, s97, s5
	s_cselect_b32 s2, s2, 0x1000
	s_lshl_b32 s6, s3, 1
	v_readlane_b32 s3, v249, 20
	s_add_i32 s2, s97, s2
	s_and_b32 s29, s29, 0xffff
	v_add_u32_e32 v145, s3, v0
	v_add_u32_e32 v146, 0x2000, v145
	v_readfirstlane_b32 s3, v145
	s_mov_b32 m0, s3
	v_readfirstlane_b32 s3, v146
	v_add_u32_e32 v147, 16, v0
	s_mul_i32 s2, s2, s5
	v_mul_lo_u32 v2, v2, s9
	buffer_load_dwordx4 v136, s[28:31], s6 offen lds
	s_mov_b32 m0, s3
	s_mul_i32 s7, s9, s70
	v_readfirstlane_b32 s3, v147
	v_add_u32_e32 v148, 0x2000, v147
	s_lshl_b32 s8, s2, 1
	v_readlane_b32 s2, v249, 21
	s_and_b32 s45, s45, 0xffff
	s_mov_b32 s46, s30
	s_mov_b32 s47, s31
	v_add_lshl_u32 v143, v3, v2, 1
	v_mul_lo_u32 v2, v4, s9
	buffer_load_dwordx4 v137, s[28:31], s6 offen lds
	s_lshl_b32 s10, s7, 1
	s_mov_b32 m0, s3
	v_readfirstlane_b32 s3, v148
	v_add_u32_e32 v150, s2, v0
	v_add_lshl_u32 v142, v5, v2, 1
	buffer_load_dwordx4 v143, s[44:47], s10 offen lds
	s_mov_b32 m0, s3
	v_readfirstlane_b32 s2, v150
	v_add_u32_e32 v151, 0x2000, v150
	buffer_load_dwordx4 v142, s[44:47], s10 offen lds
	s_mov_b32 m0, s2
	v_readfirstlane_b32 s2, v151
	buffer_load_dwordx4 v136, s[28:31], s8 offen lds
	s_mov_b32 m0, s2
	s_lshl_b32 s2, s9, 7
	v_add_u32_e32 v152, 0x4000, v147
	s_add_i32 s7, s7, s2
	v_readfirstlane_b32 s3, v152
	v_add_u32_e32 v153, 0x6000, v147
	buffer_load_dwordx4 v137, s[28:31], s8 offen lds
	s_lshl_b32 s2, s7, 1
	s_mov_b32 m0, s3
	v_readfirstlane_b32 s3, v153
	buffer_load_dwordx4 v143, s[44:47], s2 offen lds
	s_mov_b32 m0, s3
	v_ashrrev_i32_e32 v132, 8, v130
	buffer_load_dwordx4 v142, s[44:47], s2 offen lds
	v_cmp_eq_u32_e32 vcc, 1, v132
	s_and_saveexec_b64 s[2:3], vcc
	s_cbranch_execz .LBB0_191
	s_barrier
.LBB0_191:
	s_or_b64 exec, exec, s[2:3]
	v_readlane_b32 s12, v249, 22
	s_or_b32 s3, s6, 0x80
	s_waitcnt vmcnt(4)
	s_barrier
	v_add_u32_e32 v154, s12, v0
	v_add_u32_e32 v155, 0x2000, v154
	v_readfirstlane_b32 s11, v154
	s_mov_b32 m0, s11
	v_readfirstlane_b32 s11, v155
	buffer_load_dwordx4 v136, s[28:31], s3 offen lds
	s_mov_b32 m0, s11
	v_add_u32_e32 v156, 0x8000, v147
	buffer_load_dwordx4 v137, s[28:31], s3 offen lds
	v_readfirstlane_b32 s3, v156
	v_add_u32_e32 v157, 0xa000, v147
	s_bitset1_b32 s10, 7
	s_mov_b32 s46, s30
	s_mov_b32 s47, s31
	s_mov_b32 m0, s3
	v_readfirstlane_b32 s3, v157
	v_readlane_b32 s11, v249, 23
	buffer_load_dwordx4 v143, s[44:47], s10 offen lds
	s_mov_b32 m0, s3
	v_add_u32_e32 v161, s11, v0
	buffer_load_dwordx4 v142, s[44:47], s10 offen lds
	v_readfirstlane_b32 s10, v161
	v_add_u32_e32 v162, 0x2000, v161
	s_or_b32 s3, s8, 0x80
	s_mov_b32 m0, s10
	v_readfirstlane_b32 s10, v162
	buffer_load_dwordx4 v136, s[28:31], s3 offen lds
	s_mov_b32 m0, s10
	v_and_b32_e32 v131, 15, v130
	buffer_load_dwordx4 v137, s[28:31], s3 offen lds
	v_bfe_u32 v134, v130, 4, 2
	v_lshlrev_b32_e32 v4, 2, v130
	v_lshlrev_b32_e32 v2, 4, v134
	v_lshlrev_b32_e32 v3, 6, v131
	v_and_b32_e32 v4, 32, v4
	v_bitop3_b32 v3, v2, v4, v3 bitop3:0x36
	v_readlane_b32 s3, v249, 20
	v_lshrrev_b32_e32 v133, 4, v130
	s_waitcnt vmcnt(27)
	v_lshlrev_b32_e32 v11, 6, v130
	v_add_u32_e32 v5, s3, v3
	v_readlane_b32 s3, v249, 21
	s_waitcnt vmcnt(6)
	v_and_b32_e32 v135, 12, v133
	v_lshlrev_b32_e32 v10, 13, v132
	v_add_u32_e32 v6, s3, v3
	s_movk_i32 s3, 0x3c0
	v_and_or_b32 v2, v11, s3, v2
	s_add_i32 s3, s70, 0x80
	s_lshr_b32 s2, s5, 6
	v_add_u32_e32 v7, s12, v3
	v_add_u32_e32 v8, s11, v3
	v_lshlrev_b32_e32 v9, 10, v135
	v_add_u32_e32 v3, 16, v3
	v_xad_u32 v4, v2, v4, 16
	v_or_b32_e32 v11, 0x800, v10
	v_or_b32_e32 v12, 0x1000, v10
	v_or_b32_e32 v13, 0x1800, v10
	s_mul_i32 s3, s9, s3
	s_lshl_b32 s4, s4, 9
	v_mov_b32_e32 v2, 0
	s_xor_b64 s[36:37], s[36:37], -1
	s_xor_b64 s[78:79], s[54:55], -1
	s_add_i32 s2, s2, -2
	v_add_u32_e32 v159, 0xc000, v147
	v_add_u32_e32 v158, 0xe000, v147
	s_lshl_b32 s3, s3, 1
	s_mul_i32 s9, s4, s9
	s_cmp_eq_u32 s98, 2
	s_cselect_b32 s99, 0x80000, 0
	s_add_i32 s9, s9, s99
	s_mov_b32 s10, 0
	v_add_u32_e32 v163, v5, v9
	v_add_u32_e32 v141, v3, v10
	v_add_u32_e32 v140, v4, v11
	v_add_u32_e32 v139, v4, v12
	v_add_u32_e32 v138, v4, v13
	v_add_u32_e32 v160, v6, v9
	v_add_u32_e32 v149, v7, v9
	v_add_u32_e32 v144, v8, v9
	s_mov_b32 s11, 0
	v_mov_b32_e32 v3, v2
	v_mov_b32_e32 v4, v2
	v_mov_b32_e32 v5, v2
	v_mov_b32_e32 v6, v2
	v_mov_b32_e32 v7, v2
	v_mov_b32_e32 v8, v2
	v_mov_b32_e32 v9, v2
	v_mov_b32_e32 v10, v2
	v_mov_b32_e32 v11, v2
	v_mov_b32_e32 v12, v2
	v_mov_b32_e32 v13, v2
	s_waitcnt vmcnt(26)
	v_mov_b32_e32 v14, v2
	v_mov_b32_e32 v15, v2
	v_mov_b32_e32 v16, v2
	v_mov_b32_e32 v17, v2
	s_waitcnt vmcnt(25)
	v_mov_b32_e32 v18, v2
	v_mov_b32_e32 v19, v2
	v_mov_b32_e32 v20, v2
	v_mov_b32_e32 v21, v2
	s_waitcnt vmcnt(24)
	v_mov_b32_e32 v22, v2
	v_mov_b32_e32 v23, v2
	v_mov_b32_e32 v24, v2
	v_mov_b32_e32 v25, v2
	s_waitcnt vmcnt(23)
	v_mov_b32_e32 v26, v2
	v_mov_b32_e32 v27, v2
	v_mov_b32_e32 v28, v2
	v_mov_b32_e32 v29, v2
	s_waitcnt vmcnt(22)
	v_mov_b32_e32 v30, v2
	v_mov_b32_e32 v31, v2
	v_mov_b32_e32 v32, v2
	v_mov_b32_e32 v33, v2
	s_waitcnt vmcnt(14)
; #define WAIT_V(n) asm volatile("s_waitcnt vmcnt(" #n ")" ::: "memory")
; #define WAIT_L(n) asm volatile("s_waitcnt lgkmcnt(" #n ")" ::: "memory")
; #define BAR __builtin_amdgcn_s_barrier()
; #define SCHED __builtin_amdgcn_sched_barrier(0)
; DEVI void gemm256(const P& p, const u16* A, int lda, const u16* Bt, int ldb, int K, int brow, int bcol, int mode,
;                         int aux, int layer, int bmode) {
;     ...
;   f32x4 acc[2][2][4][2] = {};
;     ...
;   for (int t = 0; t < nt - 2; t += 2) {
;     LDB(B0, 0, 0); SCHED; LDA(At, 0, 0); STAGEA(SA(1, 1), brow + HALF, t + 1);
;     WAIT_L(8); BAR; WAIT_L(0); MMA(0, 0, At, B0); BAR; SCHED;
;     LDB(B1, 0, 1); STAGEB(SB(0, 0), bcol, t + 2);
;     BAR; WAIT_L(0); MMA(0, 1, At, B1); BAR;
;     LDA(At, 0, 1); STAGEA(SA(0, 0), brow, t + 2);
;     BAR; WAIT_L(0); MMA(1, 0, At, B0); BAR; SCHED;
;     STAGEB(SB(0, 1), bcol + bhalf, t + 2);
;     WAIT_V(6); BAR; MMA(1, 1, At, B1); BAR;
	v_mov_b32_e32 v62, v2
	v_mov_b32_e32 v63, v2
	v_mov_b32_e32 v64, v2
	v_mov_b32_e32 v65, v2
	v_mov_b32_e32 v82, v2
	v_mov_b32_e32 v83, v2
	v_mov_b32_e32 v84, v2
	v_mov_b32_e32 v85, v2
	v_mov_b32_e32 v98, v2
	v_mov_b32_e32 v99, v2
	v_mov_b32_e32 v100, v2
	v_mov_b32_e32 v101, v2
	v_mov_b32_e32 v110, v2
	v_mov_b32_e32 v111, v2
	v_mov_b32_e32 v112, v2
	v_mov_b32_e32 v113, v2
	v_mov_b32_e32 v114, v2
	v_mov_b32_e32 v115, v2
	v_mov_b32_e32 v116, v2
	v_mov_b32_e32 v117, v2
	v_mov_b32_e32 v118, v2
	v_mov_b32_e32 v119, v2
	v_mov_b32_e32 v120, v2
	v_mov_b32_e32 v121, v2
	v_mov_b32_e32 v122, v2
	v_mov_b32_e32 v123, v2
	v_mov_b32_e32 v124, v2
	v_mov_b32_e32 v125, v2
	v_mov_b32_e32 v126, v2
	v_mov_b32_e32 v127, v2
	v_mov_b32_e32 v128, v2
	v_mov_b32_e32 v129, v2
	v_mov_b32_e32 v34, v2
	v_mov_b32_e32 v35, v2
	v_mov_b32_e32 v36, v2
	v_mov_b32_e32 v37, v2
	v_mov_b32_e32 v38, v2
	v_mov_b32_e32 v39, v2
	v_mov_b32_e32 v40, v2
	v_mov_b32_e32 v41, v2
	v_mov_b32_e32 v42, v2
	v_mov_b32_e32 v43, v2
	v_mov_b32_e32 v44, v2
	v_mov_b32_e32 v45, v2
	v_mov_b32_e32 v46, v2
	v_mov_b32_e32 v47, v2
	v_mov_b32_e32 v48, v2
	v_mov_b32_e32 v49, v2
	v_mov_b32_e32 v50, v2
	v_mov_b32_e32 v51, v2
	v_mov_b32_e32 v52, v2
	v_mov_b32_e32 v53, v2
	v_mov_b32_e32 v54, v2
	v_mov_b32_e32 v55, v2
	v_mov_b32_e32 v56, v2
	v_mov_b32_e32 v57, v2
	v_mov_b32_e32 v58, v2
	v_mov_b32_e32 v59, v2
	v_mov_b32_e32 v60, v2
	v_mov_b32_e32 v61, v2
	v_mov_b32_e32 v70, v2
	v_mov_b32_e32 v71, v2
	v_mov_b32_e32 v72, v2
	v_mov_b32_e32 v73, v2
	v_mov_b32_e32 v66, v2
	v_mov_b32_e32 v67, v2
	v_mov_b32_e32 v68, v2
	v_mov_b32_e32 v69, v2
	v_mov_b32_e32 v74, v2
	v_mov_b32_e32 v75, v2
	v_mov_b32_e32 v76, v2
	v_mov_b32_e32 v77, v2
	v_mov_b32_e32 v78, v2
	v_mov_b32_e32 v79, v2
	v_mov_b32_e32 v80, v2
	v_mov_b32_e32 v81, v2
	v_mov_b32_e32 v86, v2
	v_mov_b32_e32 v87, v2
	v_mov_b32_e32 v88, v2
	v_mov_b32_e32 v89, v2
	v_mov_b32_e32 v90, v2
	v_mov_b32_e32 v91, v2
	v_mov_b32_e32 v92, v2
	v_mov_b32_e32 v93, v2
	v_mov_b32_e32 v94, v2
	v_mov_b32_e32 v95, v2
	v_mov_b32_e32 v96, v2
	v_mov_b32_e32 v97, v2
	v_mov_b32_e32 v102, v2
	v_mov_b32_e32 v103, v2
	v_mov_b32_e32 v104, v2
	v_mov_b32_e32 v105, v2
	v_mov_b32_e32 v106, v2
	v_mov_b32_e32 v107, v2
	v_mov_b32_e32 v108, v2
	v_mov_b32_e32 v109, v2
	s_barrier
	s_cmp_lg_u32 s98, 0
	s_cbranch_scc1 .Lhm_192
.LBB0_192:
	ds_read_b128 v[164:167], v163
	ds_read_b128 v[172:175], v163 offset:1024
	ds_read_b128 v[176:179], v163 offset:2048
	ds_read_b128 v[180:183], v163 offset:3072
	s_add_i32 s12, s3, s10
	v_readfirstlane_b32 s14, v159
	s_add_i32 s13, s12, 0x80
	s_mov_b32 m0, s14
	v_readfirstlane_b32 s14, v158
	ds_read_b128 v[184:187], v141
	ds_read_b128 v[188:191], v141 offset:1024
	ds_read_b128 v[204:207], v140
	ds_read_b128 v[208:211], v140 offset:1024
	ds_read_b128 v[212:215], v139
	ds_read_b128 v[216:219], v139 offset:1024
	ds_read_b128 v[220:223], v138
	ds_read_b128 v[224:227], v138 offset:1024
	buffer_load_dwordx4 v143, s[44:47], s13 offen lds
	s_mov_b32 m0, s14
	s_nop 0
	buffer_load_dwordx4 v142, s[44:47], s13 offen lds
	s_waitcnt lgkmcnt(8)
	s_barrier
	s_waitcnt lgkmcnt(0)
	s_setprio 1
	s_waitcnt lgkmcnt(7)
	v_mfma_f32_16x16x32_bf16 v[126:129], v[164:167], v[184:187], v[126:129]
	v_mfma_f32_16x16x32_bf16 v[122:125], v[176:179], v[184:187], v[122:125]
	s_waitcnt lgkmcnt(5)
	v_mfma_f32_16x16x32_bf16 v[118:121], v[164:167], v[204:207], v[118:121]
	v_mfma_f32_16x16x32_bf16 v[114:117], v[176:179], v[204:207], v[114:117]
	s_waitcnt lgkmcnt(3)
	v_mfma_f32_16x16x32_bf16 v[110:113], v[164:167], v[212:215], v[110:113]
	v_mfma_f32_16x16x32_bf16 v[98:101], v[176:179], v[212:215], v[98:101]
	s_waitcnt lgkmcnt(1)
	v_mfma_f32_16x16x32_bf16 v[82:85], v[164:167], v[220:223], v[82:85]
	v_mfma_f32_16x16x32_bf16 v[62:65], v[176:179], v[220:223], v[62:65]
	v_mfma_f32_16x16x32_bf16 v[126:129], v[172:175], v[188:191], v[126:129]
	v_mfma_f32_16x16x32_bf16 v[122:125], v[180:183], v[188:191], v[122:125]
	v_mfma_f32_16x16x32_bf16 v[118:121], v[172:175], v[208:211], v[118:121]
	v_mfma_f32_16x16x32_bf16 v[114:117], v[180:183], v[208:211], v[114:117]
	v_mfma_f32_16x16x32_bf16 v[110:113], v[172:175], v[216:219], v[110:113]
	v_mfma_f32_16x16x32_bf16 v[98:101], v[180:183], v[216:219], v[98:101]
	s_waitcnt lgkmcnt(0)
	v_mfma_f32_16x16x32_bf16 v[82:85], v[172:175], v[224:227], v[82:85]
	v_mfma_f32_16x16x32_bf16 v[62:65], v[180:183], v[224:227], v[62:65]
	s_setprio 0
	s_barrier
	s_add_i32 s13, s6, s10
	v_readfirstlane_b32 s15, v145
	s_add_i32 s14, s13, 0x100
	s_mov_b32 m0, s15
	v_readfirstlane_b32 s15, v146
	ds_read_b128 v[228:231], v160
	ds_read_b128 v[232:235], v160 offset:1024
	ds_read_b128 v[236:239], v160 offset:2048
	ds_read_b128 v[240:243], v160 offset:3072
	buffer_load_dwordx4 v136, s[28:31], s14 offen lds
	s_mov_b32 m0, s15
	s_add_i32 s11, s11, 2
	buffer_load_dwordx4 v137, s[28:31], s14 offen lds
	s_barrier
	s_waitcnt lgkmcnt(0)
	s_setprio 1
	s_waitcnt lgkmcnt(3)
	v_mfma_f32_16x16x32_bf16 v[30:33], v[228:231], v[184:187], v[30:33]
	s_waitcnt lgkmcnt(1)
	v_mfma_f32_16x16x32_bf16 v[26:29], v[236:239], v[184:187], v[26:29]
	v_mfma_f32_16x16x32_bf16 v[22:25], v[228:231], v[204:207], v[22:25]
	v_mfma_f32_16x16x32_bf16 v[18:21], v[236:239], v[204:207], v[18:21]
	v_mfma_f32_16x16x32_bf16 v[14:17], v[228:231], v[212:215], v[14:17]
	v_mfma_f32_16x16x32_bf16 v[10:13], v[236:239], v[212:215], v[10:13]
	v_mfma_f32_16x16x32_bf16 v[6:9], v[228:231], v[220:223], v[6:9]
	v_mfma_f32_16x16x32_bf16 v[2:5], v[236:239], v[220:223], v[2:5]
	v_mfma_f32_16x16x32_bf16 v[30:33], v[232:235], v[188:191], v[30:33]
	s_waitcnt lgkmcnt(0)
	v_mfma_f32_16x16x32_bf16 v[26:29], v[240:243], v[188:191], v[26:29]
	v_mfma_f32_16x16x32_bf16 v[22:25], v[232:235], v[208:211], v[22:25]
	v_mfma_f32_16x16x32_bf16 v[18:21], v[240:243], v[208:211], v[18:21]
	v_mfma_f32_16x16x32_bf16 v[14:17], v[232:235], v[216:219], v[14:17]
	v_mfma_f32_16x16x32_bf16 v[10:13], v[240:243], v[216:219], v[10:13]
	v_mfma_f32_16x16x32_bf16 v[6:9], v[232:235], v[224:227], v[6:9]
	v_mfma_f32_16x16x32_bf16 v[2:5], v[240:243], v[224:227], v[2:5]
	s_setprio 0
	s_add_i32 s14, s9, s10
	v_readfirstlane_b32 s16, v147
	s_add_i32 s15, s14, 0x100
	s_mov_b32 m0, s16
	v_readfirstlane_b32 s16, v148
	s_barrier
; #define WAIT_V(n) asm volatile("s_waitcnt vmcnt(" #n ")" ::: "memory")
; #define WAIT_L(n) asm volatile("s_waitcnt lgkmcnt(" #n ")" ::: "memory")
; #define BAR __builtin_amdgcn_s_barrier()
; #define SCHED __builtin_amdgcn_sched_barrier(0)
; DEVI void gemm256(const P& p, const u16* A, int lda, const u16* Bt, int ldb, int K, int brow, int bcol, int mode,
;                         int aux, int layer, int bmode) {
;     ...
;     LDB(B0, 0, 0); SCHED; LDA(At, 0, 0); STAGEA(SA(1, 1), brow + HALF, t + 1);
;     WAIT_L(8); BAR; WAIT_L(0); MMA(0, 0, At, B0); BAR; SCHED;
;     LDB(B1, 0, 1); STAGEB(SB(0, 0), bcol, t + 2);
;     BAR; WAIT_L(0); MMA(0, 1, At, B1); BAR;
;     LDA(At, 0, 1); STAGEA(SA(0, 0), brow, t + 2);
;     BAR; WAIT_L(0); MMA(1, 0, At, B0); BAR; SCHED;
;     STAGEB(SB(0, 1), bcol + bhalf, t + 2);
;     WAIT_V(6); BAR; MMA(1, 1, At, B1); BAR;
;     LDB(B0, 1, 0); SCHED; LDA(At, 1, 0); STAGEA(SA(0, 1), brow + HALF, t + 2);
;     WAIT_L(8); BAR; WAIT_L(0); MMA(0, 0, At, B0); BAR; SCHED;
;     LDB(B1, 1, 1); STAGEB(SB(1, 0), bcol, t + 3);
;     BAR; WAIT_L(0); MMA(0, 1, At, B1); BAR;
	ds_read_b128 v[184:187], v141 offset:16384
	ds_read_b128 v[188:191], v141 offset:17408
	ds_read_b128 v[204:207], v140 offset:16384
	ds_read_b128 v[208:211], v140 offset:17408
	ds_read_b128 v[212:215], v139 offset:16384
	ds_read_b128 v[216:219], v139 offset:17408
	ds_read_b128 v[220:223], v138 offset:16384
	ds_read_b128 v[224:227], v138 offset:17408
	buffer_load_dwordx4 v143, s[44:47], s15 offen lds
	s_mov_b32 m0, s16
	s_nop 0
	buffer_load_dwordx4 v142, s[44:47], s15 offen lds
	s_barrier
	s_waitcnt lgkmcnt(0)
	s_setprio 1
	s_waitcnt lgkmcnt(7)
	v_mfma_f32_16x16x32_bf16 v[34:37], v[164:167], v[184:187], v[34:37]
	v_mfma_f32_16x16x32_bf16 v[38:41], v[176:179], v[184:187], v[38:41]
	s_waitcnt lgkmcnt(5)
	v_mfma_f32_16x16x32_bf16 v[42:45], v[164:167], v[204:207], v[42:45]
	v_mfma_f32_16x16x32_bf16 v[46:49], v[176:179], v[204:207], v[46:49]
	s_waitcnt lgkmcnt(3)
	v_mfma_f32_16x16x32_bf16 v[50:53], v[164:167], v[212:215], v[50:53]
	v_mfma_f32_16x16x32_bf16 v[54:57], v[176:179], v[212:215], v[54:57]
	s_waitcnt lgkmcnt(1)
	v_mfma_f32_16x16x32_bf16 v[58:61], v[164:167], v[220:223], v[58:61]
	v_mfma_f32_16x16x32_bf16 v[70:73], v[176:179], v[220:223], v[70:73]
	v_mfma_f32_16x16x32_bf16 v[34:37], v[172:175], v[188:191], v[34:37]
	v_mfma_f32_16x16x32_bf16 v[38:41], v[180:183], v[188:191], v[38:41]
	v_mfma_f32_16x16x32_bf16 v[42:45], v[172:175], v[208:211], v[42:45]
	v_mfma_f32_16x16x32_bf16 v[46:49], v[180:183], v[208:211], v[46:49]
	v_mfma_f32_16x16x32_bf16 v[50:53], v[172:175], v[216:219], v[50:53]
	v_mfma_f32_16x16x32_bf16 v[54:57], v[180:183], v[216:219], v[54:57]
	s_waitcnt lgkmcnt(0)
	v_mfma_f32_16x16x32_bf16 v[58:61], v[172:175], v[224:227], v[58:61]
	v_mfma_f32_16x16x32_bf16 v[70:73], v[180:183], v[224:227], v[70:73]
	s_setprio 0
	s_barrier
	s_add_i32 s15, s8, s10
	v_readfirstlane_b32 s17, v150
	s_add_i32 s16, s15, 0x100
	s_mov_b32 m0, s17
	v_readfirstlane_b32 s17, v151
	buffer_load_dwordx4 v136, s[28:31], s16 offen lds
	s_mov_b32 m0, s17
	s_nop 0
	buffer_load_dwordx4 v137, s[28:31], s16 offen lds
	s_waitcnt vmcnt(6)
	s_barrier
	s_setprio 1
	v_mfma_f32_16x16x32_bf16 v[66:69], v[228:231], v[184:187], v[66:69]
	v_mfma_f32_16x16x32_bf16 v[74:77], v[236:239], v[184:187], v[74:77]
	v_mfma_f32_16x16x32_bf16 v[78:81], v[228:231], v[204:207], v[78:81]
	v_mfma_f32_16x16x32_bf16 v[86:89], v[236:239], v[204:207], v[86:89]
	v_mfma_f32_16x16x32_bf16 v[90:93], v[228:231], v[212:215], v[90:93]
	v_mfma_f32_16x16x32_bf16 v[94:97], v[236:239], v[212:215], v[94:97]
	v_mfma_f32_16x16x32_bf16 v[102:105], v[228:231], v[220:223], v[102:105]
	v_mfma_f32_16x16x32_bf16 v[106:109], v[236:239], v[220:223], v[106:109]
	v_mfma_f32_16x16x32_bf16 v[66:69], v[232:235], v[188:191], v[66:69]
	v_mfma_f32_16x16x32_bf16 v[74:77], v[240:243], v[188:191], v[74:77]
	v_mfma_f32_16x16x32_bf16 v[78:81], v[232:235], v[208:211], v[78:81]
	v_mfma_f32_16x16x32_bf16 v[86:89], v[240:243], v[208:211], v[86:89]
	v_mfma_f32_16x16x32_bf16 v[90:93], v[232:235], v[216:219], v[90:93]
	v_mfma_f32_16x16x32_bf16 v[94:97], v[240:243], v[216:219], v[94:97]
	v_mfma_f32_16x16x32_bf16 v[102:105], v[232:235], v[224:227], v[102:105]
	v_mfma_f32_16x16x32_bf16 v[106:109], v[240:243], v[224:227], v[106:109]
	s_setprio 0
	s_barrier
	ds_read_b128 v[164:167], v149
	ds_read_b128 v[172:175], v149 offset:1024
	ds_read_b128 v[176:179], v149 offset:2048
	ds_read_b128 v[180:183], v149 offset:3072
	v_readfirstlane_b32 s16, v152
	s_addk_i32 s12, 0x100
	s_mov_b32 m0, s16
	v_readfirstlane_b32 s16, v153
	ds_read_b128 v[184:187], v141 offset:32768
	ds_read_b128 v[188:191], v141 offset:33792
	ds_read_b128 v[204:207], v140 offset:32768
	ds_read_b128 v[208:211], v140 offset:33792
	ds_read_b128 v[212:215], v139 offset:32768
	ds_read_b128 v[216:219], v139 offset:33792
	ds_read_b128 v[220:223], v138 offset:32768
	ds_read_b128 v[224:227], v138 offset:33792
	buffer_load_dwordx4 v143, s[44:47], s12 offen lds
	s_mov_b32 m0, s16
	s_nop 0
	buffer_load_dwordx4 v142, s[44:47], s12 offen lds
	s_waitcnt lgkmcnt(8)
	s_barrier
	s_waitcnt lgkmcnt(0)
	s_setprio 1
	s_waitcnt lgkmcnt(7)
	v_mfma_f32_16x16x32_bf16 v[126:129], v[164:167], v[184:187], v[126:129]
	v_mfma_f32_16x16x32_bf16 v[122:125], v[176:179], v[184:187], v[122:125]
	s_waitcnt lgkmcnt(5)
	v_mfma_f32_16x16x32_bf16 v[118:121], v[164:167], v[204:207], v[118:121]
	v_mfma_f32_16x16x32_bf16 v[114:117], v[176:179], v[204:207], v[114:117]
	s_waitcnt lgkmcnt(3)
	v_mfma_f32_16x16x32_bf16 v[110:113], v[164:167], v[212:215], v[110:113]
	v_mfma_f32_16x16x32_bf16 v[98:101], v[176:179], v[212:215], v[98:101]
	s_waitcnt lgkmcnt(1)
	v_mfma_f32_16x16x32_bf16 v[82:85], v[164:167], v[220:223], v[82:85]
	v_mfma_f32_16x16x32_bf16 v[62:65], v[176:179], v[220:223], v[62:65]
	v_mfma_f32_16x16x32_bf16 v[126:129], v[172:175], v[188:191], v[126:129]
	v_mfma_f32_16x16x32_bf16 v[122:125], v[180:183], v[188:191], v[122:125]
	v_mfma_f32_16x16x32_bf16 v[118:121], v[172:175], v[208:211], v[118:121]
	v_mfma_f32_16x16x32_bf16 v[114:117], v[180:183], v[208:211], v[114:117]
	v_mfma_f32_16x16x32_bf16 v[110:113], v[172:175], v[216:219], v[110:113]
	v_mfma_f32_16x16x32_bf16 v[98:101], v[180:183], v[216:219], v[98:101]
	s_waitcnt lgkmcnt(0)
	v_mfma_f32_16x16x32_bf16 v[82:85], v[172:175], v[224:227], v[82:85]
	v_mfma_f32_16x16x32_bf16 v[62:65], v[180:183], v[224:227], v[62:65]
	s_setprio 0
	s_barrier
	v_readfirstlane_b32 s12, v154
	s_addk_i32 s13, 0x180
	s_mov_b32 m0, s12
	v_readfirstlane_b32 s12, v155
	ds_read_b128 v[228:231], v144
	ds_read_b128 v[232:235], v144 offset:1024
	ds_read_b128 v[236:239], v144 offset:2048
	ds_read_b128 v[240:243], v144 offset:3072
	buffer_load_dwordx4 v136, s[28:31], s13 offen lds
	s_mov_b32 m0, s12
	s_nop 0
	buffer_load_dwordx4 v137, s[28:31], s13 offen lds
	s_barrier
; #define WAIT_V(n) asm volatile("s_waitcnt vmcnt(" #n ")" ::: "memory")
; #define WAIT_L(n) asm volatile("s_waitcnt lgkmcnt(" #n ")" ::: "memory")
; #define BAR __builtin_amdgcn_s_barrier()
; #define SCHED __builtin_amdgcn_sched_barrier(0)
; DEVI void gemm256(const P& p, const u16* A, int lda, const u16* Bt, int ldb, int K, int brow, int bcol, int mode,
;                         int aux, int layer, int bmode) {
;     ...
;     WAIT_L(8); BAR; WAIT_L(0); MMA(0, 0, At, B0); BAR; SCHED;
;     LDB(B1, 1, 1); STAGEB(SB(1, 0), bcol, t + 3);
;     BAR; WAIT_L(0); MMA(0, 1, At, B1); BAR;
;     LDA(At, 1, 1); STAGEA(SA(1, 0), brow, t + 3);
;     BAR; WAIT_L(0); MMA(1, 0, At, B0); BAR; SCHED;
;     STAGEB(SB(1, 1), bcol + bhalf, t + 3);
;     WAIT_V(6); BAR; MMA(1, 1, At, B1); BAR;
;   }
;   {
;     LDB(B0, 0, 0); LDA(At, 0, 0); STAGEA(SA(1, 1), brow + HALF, nt - 1);
	s_waitcnt lgkmcnt(0)
	s_setprio 1
	s_waitcnt lgkmcnt(3)
	v_mfma_f32_16x16x32_bf16 v[30:33], v[228:231], v[184:187], v[30:33]
	s_waitcnt lgkmcnt(1)
	v_mfma_f32_16x16x32_bf16 v[26:29], v[236:239], v[184:187], v[26:29]
	v_mfma_f32_16x16x32_bf16 v[22:25], v[228:231], v[204:207], v[22:25]
	v_mfma_f32_16x16x32_bf16 v[18:21], v[236:239], v[204:207], v[18:21]
	v_mfma_f32_16x16x32_bf16 v[14:17], v[228:231], v[212:215], v[14:17]
	v_mfma_f32_16x16x32_bf16 v[10:13], v[236:239], v[212:215], v[10:13]
	v_mfma_f32_16x16x32_bf16 v[6:9], v[228:231], v[220:223], v[6:9]
	v_mfma_f32_16x16x32_bf16 v[2:5], v[236:239], v[220:223], v[2:5]
	v_mfma_f32_16x16x32_bf16 v[30:33], v[232:235], v[188:191], v[30:33]
	s_waitcnt lgkmcnt(0)
	v_mfma_f32_16x16x32_bf16 v[26:29], v[240:243], v[188:191], v[26:29]
	v_mfma_f32_16x16x32_bf16 v[22:25], v[232:235], v[208:211], v[22:25]
	v_mfma_f32_16x16x32_bf16 v[18:21], v[240:243], v[208:211], v[18:21]
	v_mfma_f32_16x16x32_bf16 v[14:17], v[232:235], v[216:219], v[14:17]
	v_mfma_f32_16x16x32_bf16 v[10:13], v[240:243], v[216:219], v[10:13]
	v_mfma_f32_16x16x32_bf16 v[6:9], v[232:235], v[224:227], v[6:9]
	v_mfma_f32_16x16x32_bf16 v[2:5], v[240:243], v[224:227], v[2:5]
	s_setprio 0
	v_readfirstlane_b32 s12, v156
	s_addk_i32 s14, 0x180
	s_mov_b32 m0, s12
	v_readfirstlane_b32 s12, v157
	s_barrier
	ds_read_b128 v[184:187], v141 offset:49152
	ds_read_b128 v[188:191], v141 offset:50176
	ds_read_b128 v[204:207], v140 offset:49152
	ds_read_b128 v[208:211], v140 offset:50176
	ds_read_b128 v[212:215], v139 offset:49152
	ds_read_b128 v[216:219], v139 offset:50176
	ds_read_b128 v[220:223], v138 offset:49152
	ds_read_b128 v[224:227], v138 offset:50176
	buffer_load_dwordx4 v143, s[44:47], s14 offen lds
	s_mov_b32 m0, s12
	s_nop 0
	buffer_load_dwordx4 v142, s[44:47], s14 offen lds
	s_barrier
	s_waitcnt lgkmcnt(0)
	s_setprio 1
	s_waitcnt lgkmcnt(7)
	v_mfma_f32_16x16x32_bf16 v[34:37], v[164:167], v[184:187], v[34:37]
	v_mfma_f32_16x16x32_bf16 v[38:41], v[176:179], v[184:187], v[38:41]
	s_waitcnt lgkmcnt(5)
	v_mfma_f32_16x16x32_bf16 v[42:45], v[164:167], v[204:207], v[42:45]
	v_mfma_f32_16x16x32_bf16 v[46:49], v[176:179], v[204:207], v[46:49]
	s_waitcnt lgkmcnt(3)
	v_mfma_f32_16x16x32_bf16 v[50:53], v[164:167], v[212:215], v[50:53]
	v_mfma_f32_16x16x32_bf16 v[54:57], v[176:179], v[212:215], v[54:57]
	s_waitcnt lgkmcnt(1)
	v_mfma_f32_16x16x32_bf16 v[58:61], v[164:167], v[220:223], v[58:61]
	v_mfma_f32_16x16x32_bf16 v[70:73], v[176:179], v[220:223], v[70:73]
	v_mfma_f32_16x16x32_bf16 v[34:37], v[172:175], v[188:191], v[34:37]
	v_mfma_f32_16x16x32_bf16 v[38:41], v[180:183], v[188:191], v[38:41]
	v_mfma_f32_16x16x32_bf16 v[42:45], v[172:175], v[208:211], v[42:45]
	v_mfma_f32_16x16x32_bf16 v[46:49], v[180:183], v[208:211], v[46:49]
	v_mfma_f32_16x16x32_bf16 v[50:53], v[172:175], v[216:219], v[50:53]
	v_mfma_f32_16x16x32_bf16 v[54:57], v[180:183], v[216:219], v[54:57]
	s_waitcnt lgkmcnt(0)
	v_mfma_f32_16x16x32_bf16 v[58:61], v[172:175], v[224:227], v[58:61]
	v_mfma_f32_16x16x32_bf16 v[70:73], v[180:183], v[224:227], v[70:73]
	s_setprio 0
	s_barrier
	v_readfirstlane_b32 s12, v161
	s_addk_i32 s15, 0x180
	s_mov_b32 m0, s12
	v_readfirstlane_b32 s12, v162
	buffer_load_dwordx4 v136, s[28:31], s15 offen lds
	s_mov_b32 m0, s12
	s_nop 0
	buffer_load_dwordx4 v137, s[28:31], s15 offen lds
	s_waitcnt vmcnt(6)
	s_barrier
	s_setprio 1
	v_mfma_f32_16x16x32_bf16 v[66:69], v[228:231], v[184:187], v[66:69]
	v_mfma_f32_16x16x32_bf16 v[74:77], v[236:239], v[184:187], v[74:77]
	v_mfma_f32_16x16x32_bf16 v[78:81], v[228:231], v[204:207], v[78:81]
	v_mfma_f32_16x16x32_bf16 v[86:89], v[236:239], v[204:207], v[86:89]
	v_mfma_f32_16x16x32_bf16 v[90:93], v[228:231], v[212:215], v[90:93]
	v_mfma_f32_16x16x32_bf16 v[94:97], v[236:239], v[212:215], v[94:97]
	v_mfma_f32_16x16x32_bf16 v[102:105], v[228:231], v[220:223], v[102:105]
	v_mfma_f32_16x16x32_bf16 v[106:109], v[236:239], v[220:223], v[106:109]
	v_mfma_f32_16x16x32_bf16 v[66:69], v[232:235], v[188:191], v[66:69]
	v_mfma_f32_16x16x32_bf16 v[74:77], v[240:243], v[188:191], v[74:77]
	v_mfma_f32_16x16x32_bf16 v[78:81], v[232:235], v[208:211], v[78:81]
	v_mfma_f32_16x16x32_bf16 v[86:89], v[240:243], v[208:211], v[86:89]
	v_mfma_f32_16x16x32_bf16 v[90:93], v[232:235], v[216:219], v[90:93]
	v_mfma_f32_16x16x32_bf16 v[94:97], v[240:243], v[216:219], v[94:97]
	v_mfma_f32_16x16x32_bf16 v[102:105], v[232:235], v[224:227], v[102:105]
	v_mfma_f32_16x16x32_bf16 v[106:109], v[240:243], v[224:227], v[106:109]
	s_setprio 0
	s_addk_i32 s10, 0x100
	s_cmp_lt_u32 s11, s2
	s_barrier
	s_cbranch_scc1 .LBB0_192
	s_add_i32 s2, s5, s7
	s_lshl_b32 s2, s2, 1
	v_readfirstlane_b32 s3, v159
	s_addk_i32 s2, 0xff80
	s_mov_b32 s46, s30
	s_mov_b32 s47, s31
	s_mov_b32 m0, s3
	v_readfirstlane_b32 s3, v158
	ds_read_b128 v[150:153], v163
	ds_read_b128 v[154:157], v163 offset:1024
	ds_read_b128 v[164:167], v163 offset:2048
	ds_read_b128 v[172:175], v163 offset:3072
	ds_read_b128 v[176:179], v141
	ds_read_b128 v[180:183], v141 offset:1024
	ds_read_b128 v[184:187], v140
	ds_read_b128 v[188:191], v140 offset:1024
	ds_read_b128 v[204:207], v139
	ds_read_b128 v[208:211], v139 offset:1024
	ds_read_b128 v[212:215], v138
	ds_read_b128 v[216:219], v138 offset:1024
	buffer_load_dwordx4 v143, s[44:47], s2 offen lds
	s_mov_b32 m0, s3
	s_nop 0
	buffer_load_dwordx4 v142, s[44:47], s2 offen lds
	s_barrier
; #define WAIT_V(n) asm volatile("s_waitcnt vmcnt(" #n ")" ::: "memory")
; #define WAIT_L(n) asm volatile("s_waitcnt lgkmcnt(" #n ")" ::: "memory")
; #define BAR __builtin_amdgcn_s_barrier()
; DEVI void gemm256(const P& p, const u16* A, int lda, const u16* Bt, int ldb, int K, int brow, int bcol, int mode,
;                         int aux, int layer, int bmode) {
;     ...
;     LDB(B0, 0, 0); LDA(At, 0, 0); STAGEA(SA(1, 1), brow + HALF, nt - 1);
;     BAR; WAIT_L(0); MMA(0, 0, At, B0); BAR;
;     LDB(B1, 0, 1); BAR; WAIT_L(0); MMA(0, 1, At, B1); BAR;
;     LDA(At, 0, 1); WAIT_V(4); BAR; WAIT_L(0); MMA(1, 0, At, B0); MMA(1, 1, At, B1); BAR;
;   }
;   {
;     LDB(B0, 1, 0); LDA(At, 1, 0); WAIT_V(2); BAR; WAIT_L(0); MMA(0, 0, At, B0); BAR;
	s_waitcnt lgkmcnt(0)
	s_setprio 1
	s_waitcnt lgkmcnt(7)
	v_mfma_f32_16x16x32_bf16 v[126:129], v[150:153], v[176:179], v[126:129]
	v_mfma_f32_16x16x32_bf16 v[122:125], v[164:167], v[176:179], v[122:125]
	s_waitcnt lgkmcnt(5)
	v_mfma_f32_16x16x32_bf16 v[118:121], v[150:153], v[184:187], v[118:121]
	v_mfma_f32_16x16x32_bf16 v[114:117], v[164:167], v[184:187], v[114:117]
	s_waitcnt lgkmcnt(3)
	v_mfma_f32_16x16x32_bf16 v[110:113], v[150:153], v[204:207], v[110:113]
	v_mfma_f32_16x16x32_bf16 v[98:101], v[164:167], v[204:207], v[98:101]
	s_waitcnt lgkmcnt(1)
	v_mfma_f32_16x16x32_bf16 v[82:85], v[150:153], v[212:215], v[82:85]
	v_mfma_f32_16x16x32_bf16 v[62:65], v[164:167], v[212:215], v[62:65]
	v_mfma_f32_16x16x32_bf16 v[126:129], v[154:157], v[180:183], v[126:129]
	v_mfma_f32_16x16x32_bf16 v[122:125], v[172:175], v[180:183], v[122:125]
	v_mfma_f32_16x16x32_bf16 v[118:121], v[154:157], v[188:191], v[118:121]
	v_mfma_f32_16x16x32_bf16 v[114:117], v[172:175], v[188:191], v[114:117]
	v_mfma_f32_16x16x32_bf16 v[110:113], v[154:157], v[208:211], v[110:113]
	v_mfma_f32_16x16x32_bf16 v[98:101], v[172:175], v[208:211], v[98:101]
	s_waitcnt lgkmcnt(0)
	v_mfma_f32_16x16x32_bf16 v[82:85], v[154:157], v[216:219], v[82:85]
	v_mfma_f32_16x16x32_bf16 v[62:65], v[172:175], v[216:219], v[62:65]
	s_setprio 0
	s_barrier
	ds_read_b128 v[220:223], v160
	ds_read_b128 v[224:227], v160 offset:1024
	ds_read_b128 v[228:231], v160 offset:2048
	ds_read_b128 v[158:161], v160 offset:3072
	s_barrier
	s_waitcnt lgkmcnt(0)
	s_setprio 1
	s_waitcnt lgkmcnt(3)
	v_mfma_f32_16x16x32_bf16 v[30:33], v[220:223], v[176:179], v[30:33]
	s_waitcnt lgkmcnt(1)
	v_mfma_f32_16x16x32_bf16 v[26:29], v[228:231], v[176:179], v[26:29]
	v_mfma_f32_16x16x32_bf16 v[22:25], v[220:223], v[184:187], v[22:25]
	v_mfma_f32_16x16x32_bf16 v[18:21], v[228:231], v[184:187], v[18:21]
	v_mfma_f32_16x16x32_bf16 v[14:17], v[220:223], v[204:207], v[14:17]
	v_mfma_f32_16x16x32_bf16 v[10:13], v[228:231], v[204:207], v[10:13]
	v_mfma_f32_16x16x32_bf16 v[6:9], v[220:223], v[212:215], v[6:9]
	v_mfma_f32_16x16x32_bf16 v[2:5], v[228:231], v[212:215], v[2:5]
	v_mfma_f32_16x16x32_bf16 v[30:33], v[224:227], v[180:183], v[30:33]
	s_waitcnt lgkmcnt(0)
	v_mfma_f32_16x16x32_bf16 v[26:29], v[158:161], v[180:183], v[26:29]
	v_mfma_f32_16x16x32_bf16 v[22:25], v[224:227], v[188:191], v[22:25]
	v_mfma_f32_16x16x32_bf16 v[18:21], v[158:161], v[188:191], v[18:21]
	v_mfma_f32_16x16x32_bf16 v[14:17], v[224:227], v[208:211], v[14:17]
	v_mfma_f32_16x16x32_bf16 v[10:13], v[158:161], v[208:211], v[10:13]
	v_mfma_f32_16x16x32_bf16 v[6:9], v[224:227], v[216:219], v[6:9]
	v_mfma_f32_16x16x32_bf16 v[2:5], v[158:161], v[216:219], v[2:5]
	s_setprio 0
	s_barrier
	ds_read_b128 v[176:179], v141 offset:16384
	ds_read_b128 v[180:183], v141 offset:17408
	ds_read_b128 v[184:187], v140 offset:16384
	ds_read_b128 v[188:191], v140 offset:17408
	ds_read_b128 v[204:207], v139 offset:16384
	ds_read_b128 v[208:211], v139 offset:17408
	ds_read_b128 v[212:215], v138 offset:16384
	ds_read_b128 v[216:219], v138 offset:17408
	s_waitcnt vmcnt(4)
	s_barrier
	s_waitcnt lgkmcnt(0)
	s_setprio 1
	s_waitcnt lgkmcnt(3)
	v_mfma_f32_16x16x32_bf16 v[50:53], v[150:153], v[204:207], v[50:53]
	s_waitcnt lgkmcnt(2)
	v_mfma_f32_16x16x32_bf16 v[232:235], v[154:157], v[208:211], v[50:53]
	v_mfma_f32_16x16x32_bf16 v[50:53], v[164:167], v[204:207], v[54:57]
	v_mfma_f32_16x16x32_bf16 v[34:37], v[150:153], v[176:179], v[34:37]
	v_mfma_f32_16x16x32_bf16 v[38:41], v[164:167], v[176:179], v[38:41]
	v_mfma_f32_16x16x32_bf16 v[42:45], v[150:153], v[184:187], v[42:45]
	v_mfma_f32_16x16x32_bf16 v[46:49], v[164:167], v[184:187], v[46:49]
	v_mfma_f32_16x16x32_bf16 v[236:239], v[172:175], v[208:211], v[50:53]
	s_waitcnt lgkmcnt(1)
	v_mfma_f32_16x16x32_bf16 v[50:53], v[150:153], v[212:215], v[58:61]
	v_mfma_f32_16x16x32_bf16 v[34:37], v[154:157], v[180:183], v[34:37]
	v_mfma_f32_16x16x32_bf16 v[38:41], v[172:175], v[180:183], v[38:41]
	v_mfma_f32_16x16x32_bf16 v[42:45], v[154:157], v[188:191], v[42:45]
	v_mfma_f32_16x16x32_bf16 v[46:49], v[172:175], v[188:191], v[46:49]
	s_waitcnt lgkmcnt(0)
	v_mfma_f32_16x16x32_bf16 v[150:153], v[154:157], v[216:219], v[50:53]
	v_mfma_f32_16x16x32_bf16 v[50:53], v[164:167], v[212:215], v[70:73]
	v_mfma_f32_16x16x32_bf16 v[154:157], v[172:175], v[216:219], v[50:53]
	s_setprio 0
	s_setprio 1
	v_mfma_f32_16x16x32_bf16 v[50:53], v[220:223], v[176:179], v[66:69]
	v_mfma_f32_16x16x32_bf16 v[162:165], v[224:227], v[180:183], v[50:53]
	v_mfma_f32_16x16x32_bf16 v[50:53], v[228:231], v[176:179], v[74:77]
	v_mfma_f32_16x16x32_bf16 v[166:169], v[158:161], v[180:183], v[50:53]
	v_mfma_f32_16x16x32_bf16 v[50:53], v[220:223], v[184:187], v[78:81]
	v_mfma_f32_16x16x32_bf16 v[172:175], v[224:227], v[188:191], v[50:53]
	v_mfma_f32_16x16x32_bf16 v[50:53], v[228:231], v[184:187], v[86:89]
	v_mfma_f32_16x16x32_bf16 v[176:179], v[158:161], v[188:191], v[50:53]
	v_mfma_f32_16x16x32_bf16 v[50:53], v[220:223], v[204:207], v[90:93]
	v_mfma_f32_16x16x32_bf16 v[180:183], v[224:227], v[208:211], v[50:53]
	v_mfma_f32_16x16x32_bf16 v[50:53], v[228:231], v[204:207], v[94:97]
	v_mfma_f32_16x16x32_bf16 v[184:187], v[158:161], v[208:211], v[50:53]
	v_mfma_f32_16x16x32_bf16 v[50:53], v[220:223], v[212:215], v[102:105]
	v_mfma_f32_16x16x32_bf16 v[188:191], v[224:227], v[216:219], v[50:53]
	v_mfma_f32_16x16x32_bf16 v[50:53], v[228:231], v[212:215], v[106:109]
	v_mfma_f32_16x16x32_bf16 v[158:161], v[158:161], v[216:219], v[50:53]
	s_setprio 0
	s_barrier
; #define WAIT_V(n) asm volatile("s_waitcnt vmcnt(" #n ")" ::: "memory")
; #define WAIT_L(n) asm volatile("s_waitcnt lgkmcnt(" #n ")" ::: "memory")
; #define BAR __builtin_amdgcn_s_barrier()
; DEVI void gemm256(const P& p, const u16* A, int lda, const u16* Bt, int ldb, int K, int brow, int bcol, int mode,
;                         int aux, int layer, int bmode) {
;     ...
;     LDB(B0, 1, 0); LDA(At, 1, 0); WAIT_V(2); BAR; WAIT_L(0); MMA(0, 0, At, B0); BAR;
;     LDB(B1, 1, 1); WAIT_V(0); BAR; WAIT_L(0); MMA(0, 1, At, B1); BAR;
;     LDA(At, 1, 1); BAR; WAIT_L(0); MMA(1, 0, At, B0); MMA(1, 1, At, B1); BAR;
;   }
;   if (wr == 0) BAR;
	ds_read_b128 v[204:207], v149
	ds_read_b128 v[208:211], v149 offset:1024
	ds_read_b128 v[212:215], v149 offset:2048
	ds_read_b128 v[146:149], v149 offset:3072
	s_nop 0
	ds_read_b128 v[50:53], v141 offset:32768
	ds_read_b128 v[54:57], v141 offset:33792
	ds_read_b128 v[58:61], v140 offset:32768
	ds_read_b128 v[66:69], v140 offset:33792
	ds_read_b128 v[70:73], v139 offset:32768
	ds_read_b128 v[78:81], v139 offset:33792
	ds_read_b128 v[216:219], v138 offset:32768
	ds_read_b128 v[220:223], v138 offset:33792
	s_waitcnt vmcnt(2)
	s_barrier
	s_waitcnt lgkmcnt(0)
	s_setprio 1
	s_waitcnt lgkmcnt(7)
	v_mfma_f32_16x16x32_bf16 v[74:77], v[204:207], v[50:53], v[126:129]
	s_waitcnt lgkmcnt(6)
	v_mfma_f32_16x16x32_bf16 v[126:129], v[208:211], v[54:57], v[74:77]
	v_mfma_f32_16x16x32_bf16 v[74:77], v[212:215], v[50:53], v[122:125]
	v_mfma_f32_16x16x32_bf16 v[122:125], v[146:149], v[54:57], v[74:77]
	s_waitcnt lgkmcnt(5)
	v_mfma_f32_16x16x32_bf16 v[74:77], v[204:207], v[58:61], v[118:121]
	s_waitcnt lgkmcnt(4)
	v_mfma_f32_16x16x32_bf16 v[118:121], v[208:211], v[66:69], v[74:77]
	v_mfma_f32_16x16x32_bf16 v[74:77], v[212:215], v[58:61], v[114:117]
	v_mfma_f32_16x16x32_bf16 v[114:117], v[146:149], v[66:69], v[74:77]
	s_waitcnt lgkmcnt(3)
	v_mfma_f32_16x16x32_bf16 v[74:77], v[204:207], v[70:73], v[110:113]
	s_waitcnt lgkmcnt(2)
	v_mfma_f32_16x16x32_bf16 v[110:113], v[208:211], v[78:81], v[74:77]
	v_mfma_f32_16x16x32_bf16 v[74:77], v[212:215], v[70:73], v[98:101]
	v_mfma_f32_16x16x32_bf16 v[102:105], v[146:149], v[78:81], v[74:77]
	s_waitcnt lgkmcnt(1)
	v_mfma_f32_16x16x32_bf16 v[74:77], v[204:207], v[216:219], v[82:85]
	v_mfma_f32_16x16x32_bf16 v[62:65], v[212:215], v[216:219], v[62:65]
	s_waitcnt lgkmcnt(0)
	v_mfma_f32_16x16x32_bf16 v[98:101], v[208:211], v[220:223], v[74:77]
	v_mfma_f32_16x16x32_bf16 v[90:93], v[146:149], v[220:223], v[62:65]
	s_setprio 0
	s_barrier
	ds_read_b128 v[224:227], v144
	ds_read_b128 v[228:231], v144 offset:1024
	ds_read_b128 v[240:243], v144 offset:2048
	ds_read_b128 v[142:145], v144 offset:3072
	s_waitcnt vmcnt(0)
	s_barrier
	s_waitcnt lgkmcnt(0)
	s_setprio 1
	s_waitcnt lgkmcnt(3)
	v_mfma_f32_16x16x32_bf16 v[30:33], v[224:227], v[50:53], v[30:33]
	s_waitcnt lgkmcnt(1)
	v_mfma_f32_16x16x32_bf16 v[26:29], v[240:243], v[50:53], v[26:29]
	v_mfma_f32_16x16x32_bf16 v[22:25], v[224:227], v[58:61], v[22:25]
	v_mfma_f32_16x16x32_bf16 v[18:21], v[240:243], v[58:61], v[18:21]
	v_mfma_f32_16x16x32_bf16 v[14:17], v[224:227], v[70:73], v[14:17]
	v_mfma_f32_16x16x32_bf16 v[10:13], v[240:243], v[70:73], v[10:13]
	v_mfma_f32_16x16x32_bf16 v[6:9], v[224:227], v[216:219], v[6:9]
	v_mfma_f32_16x16x32_bf16 v[2:5], v[240:243], v[216:219], v[2:5]
	v_mfma_f32_16x16x32_bf16 v[106:109], v[228:231], v[54:57], v[30:33]
	s_waitcnt lgkmcnt(0)
	v_mfma_f32_16x16x32_bf16 v[94:97], v[142:145], v[54:57], v[26:29]
	v_mfma_f32_16x16x32_bf16 v[86:89], v[228:231], v[66:69], v[22:25]
	v_mfma_f32_16x16x32_bf16 v[82:85], v[142:145], v[66:69], v[18:21]
	v_mfma_f32_16x16x32_bf16 v[74:77], v[228:231], v[78:81], v[14:17]
	v_mfma_f32_16x16x32_bf16 v[66:69], v[142:145], v[78:81], v[10:13]
	v_mfma_f32_16x16x32_bf16 v[62:65], v[228:231], v[220:223], v[6:9]
	v_mfma_f32_16x16x32_bf16 v[54:57], v[142:145], v[220:223], v[2:5]
	s_setprio 0
	s_barrier
	s_nop 0
	ds_read_b128 v[2:5], v141 offset:49152
	ds_read_b128 v[6:9], v141 offset:50176
	ds_read_b128 v[10:13], v140 offset:49152
	ds_read_b128 v[14:17], v140 offset:50176
	ds_read_b128 v[216:219], v139 offset:49152
	ds_read_b128 v[220:223], v139 offset:50176
	ds_read_b128 v[244:247], v138 offset:49152
	ds_read_b128 v[136:139], v138 offset:50176
	s_barrier
	s_waitcnt lgkmcnt(0)
	s_setprio 1
	s_waitcnt lgkmcnt(7)
	v_mfma_f32_16x16x32_bf16 v[18:21], v[204:207], v[2:5], v[34:37]
	s_waitcnt lgkmcnt(6)
	v_mfma_f32_16x16x32_bf16 v[78:81], v[208:211], v[6:9], v[18:21]
	v_mfma_f32_16x16x32_bf16 v[18:21], v[212:215], v[2:5], v[38:41]
	v_mfma_f32_16x16x32_bf16 v[70:73], v[146:149], v[6:9], v[18:21]
	s_waitcnt lgkmcnt(5)
	v_mfma_f32_16x16x32_bf16 v[18:21], v[204:207], v[10:13], v[42:45]
	s_waitcnt lgkmcnt(4)
	v_mfma_f32_16x16x32_bf16 v[58:61], v[208:211], v[14:17], v[18:21]
	v_mfma_f32_16x16x32_bf16 v[18:21], v[212:215], v[10:13], v[46:49]
	v_mfma_f32_16x16x32_bf16 v[50:53], v[146:149], v[14:17], v[18:21]
	s_waitcnt lgkmcnt(3)
	v_mfma_f32_16x16x32_bf16 v[18:21], v[204:207], v[216:219], v[232:235]
	s_waitcnt lgkmcnt(2)
	v_mfma_f32_16x16x32_bf16 v[46:49], v[208:211], v[220:223], v[18:21]
	v_mfma_f32_16x16x32_bf16 v[18:21], v[212:215], v[216:219], v[236:239]
	v_mfma_f32_16x16x32_bf16 v[42:45], v[146:149], v[220:223], v[18:21]
	s_waitcnt lgkmcnt(1)
	v_mfma_f32_16x16x32_bf16 v[18:21], v[204:207], v[244:247], v[150:153]
	s_waitcnt lgkmcnt(0)
	v_mfma_f32_16x16x32_bf16 v[38:41], v[208:211], v[136:139], v[18:21]
	v_mfma_f32_16x16x32_bf16 v[18:21], v[212:215], v[244:247], v[154:157]
	v_mfma_f32_16x16x32_bf16 v[34:37], v[146:149], v[136:139], v[18:21]
	s_setprio 0
	s_setprio 1
	v_mfma_f32_16x16x32_bf16 v[18:21], v[224:227], v[2:5], v[162:165]
	v_mfma_f32_16x16x32_bf16 v[2:5], v[240:243], v[2:5], v[166:169]
	v_mfma_f32_16x16x32_bf16 v[26:29], v[142:145], v[6:9], v[2:5]
	v_mfma_f32_16x16x32_bf16 v[2:5], v[224:227], v[10:13], v[172:175]
	v_mfma_f32_16x16x32_bf16 v[22:25], v[228:231], v[14:17], v[2:5]
	v_mfma_f32_16x16x32_bf16 v[2:5], v[240:243], v[10:13], v[176:179]
	v_mfma_f32_16x16x32_bf16 v[30:33], v[228:231], v[6:9], v[18:21]
	v_mfma_f32_16x16x32_bf16 v[18:21], v[142:145], v[14:17], v[2:5]
	v_mfma_f32_16x16x32_bf16 v[2:5], v[224:227], v[216:219], v[180:183]
	v_mfma_f32_16x16x32_bf16 v[14:17], v[228:231], v[220:223], v[2:5]
	v_mfma_f32_16x16x32_bf16 v[2:5], v[240:243], v[216:219], v[184:187]
	v_mfma_f32_16x16x32_bf16 v[10:13], v[142:145], v[220:223], v[2:5]
	v_mfma_f32_16x16x32_bf16 v[2:5], v[224:227], v[244:247], v[188:191]
	v_mfma_f32_16x16x32_bf16 v[6:9], v[228:231], v[136:139], v[2:5]
	v_mfma_f32_16x16x32_bf16 v[2:5], v[240:243], v[244:247], v[158:161]
	v_mfma_f32_16x16x32_bf16 v[2:5], v[142:145], v[136:139], v[2:5]
	s_setprio 0
	s_branch .Lhm_join
; #define WAIT_V(n) asm volatile("s_waitcnt vmcnt(" #n ")" ::: "memory")
; #define WAIT_L(n) asm volatile("s_waitcnt lgkmcnt(" #n ")" ::: "memory")
; #define BAR __builtin_amdgcn_s_barrier()
; #define SCHED __builtin_amdgcn_sched_barrier(0)
; DEVI void gemm256(const P& p, const u16* A, int lda, const u16* Bt, int ldb, int K, int brow, int bcol, int mode,
;                         int aux, int layer, int bmode) {
;     ...
;   for (int t = 0; t < nt - 2; t += 2) {
;     LDB(B0, 0, 0); SCHED; LDA(At, 0, 0); STAGEA(SA(1, 1), brow + HALF, t + 1);
;     WAIT_L(8); BAR; WAIT_L(0); MMA(0, 0, At, B0); BAR; SCHED;
;     LDB(B1, 0, 1); STAGEB(SB(0, 0), bcol, t + 2);
;     BAR; WAIT_L(0); MMA(0, 1, At, B1); BAR;
;     LDA(At, 0, 1); STAGEA(SA(0, 0), brow, t + 2);
;     BAR; WAIT_L(0); MMA(1, 0, At, B0); BAR; SCHED;
;     STAGEB(SB(0, 1), bcol + bhalf, t + 2);
;     WAIT_V(6); BAR; MMA(1, 1, At, B1); BAR;
;     LDB(B0, 1, 0); SCHED; LDA(At, 1, 0); STAGEA(SA(0, 1), brow + HALF, t + 2);
;     WAIT_L(8); BAR; WAIT_L(0); MMA(0, 0, At, B0); BAR; SCHED;
;     LDB(B1, 1, 1); STAGEB(SB(1, 0), bcol, t + 3);
;     BAR; WAIT_L(0); MMA(0, 1, At, B1); BAR;
.Lhm_192:
	ds_read_b128 v[164:167], v163
	ds_read_b128 v[172:175], v163 offset:1024
	ds_read_b128 v[176:179], v163 offset:2048
	ds_read_b128 v[180:183], v163 offset:3072
	s_add_i32 s12, s3, s10
	v_readfirstlane_b32 s14, v159
	s_add_i32 s13, s12, 0x80
	s_mov_b32 m0, s14
	v_readfirstlane_b32 s14, v158
	ds_read_b128 v[184:187], v141
	ds_read_b128 v[188:191], v141 offset:1024
	ds_read_b128 v[204:207], v140
	ds_read_b128 v[208:211], v140 offset:1024
	ds_read_b128 v[212:215], v139
	ds_read_b128 v[216:219], v139 offset:1024
	ds_read_b128 v[220:223], v138
	ds_read_b128 v[224:227], v138 offset:1024
	buffer_load_dwordx4 v143, s[44:47], s13 offen lds
	s_mov_b32 m0, s14
	s_nop 0
	buffer_load_dwordx4 v142, s[44:47], s13 offen lds
	s_waitcnt lgkmcnt(8)
	s_barrier
	s_waitcnt lgkmcnt(0)
	s_setprio 1
	s_waitcnt lgkmcnt(7)
	v_mfma_f32_16x16x32_bf16 v[126:129], v[164:167], v[184:187], v[126:129]
	v_mfma_f32_16x16x32_bf16 v[122:125], v[176:179], v[184:187], v[122:125]
	s_waitcnt lgkmcnt(5)
	v_mfma_f32_16x16x32_bf16 v[118:121], v[164:167], v[204:207], v[118:121]
	v_mfma_f32_16x16x32_bf16 v[114:117], v[176:179], v[204:207], v[114:117]
	s_waitcnt lgkmcnt(3)
	v_mfma_f32_16x16x32_bf16 v[110:113], v[164:167], v[212:215], v[110:113]
	v_mfma_f32_16x16x32_bf16 v[98:101], v[176:179], v[212:215], v[98:101]
	s_waitcnt lgkmcnt(1)
	v_mfma_f32_16x16x32_bf16 v[82:85], v[164:167], v[220:223], v[82:85]
	v_mfma_f32_16x16x32_bf16 v[62:65], v[176:179], v[220:223], v[62:65]
	v_mfma_f32_16x16x32_bf16 v[126:129], v[172:175], v[188:191], v[126:129]
	v_mfma_f32_16x16x32_bf16 v[122:125], v[180:183], v[188:191], v[122:125]
	v_mfma_f32_16x16x32_bf16 v[118:121], v[172:175], v[208:211], v[118:121]
	v_mfma_f32_16x16x32_bf16 v[114:117], v[180:183], v[208:211], v[114:117]
	v_mfma_f32_16x16x32_bf16 v[110:113], v[172:175], v[216:219], v[110:113]
	v_mfma_f32_16x16x32_bf16 v[98:101], v[180:183], v[216:219], v[98:101]
	s_waitcnt lgkmcnt(0)
	v_mfma_f32_16x16x32_bf16 v[82:85], v[172:175], v[224:227], v[82:85]
	v_mfma_f32_16x16x32_bf16 v[62:65], v[180:183], v[224:227], v[62:65]
	s_setprio 0
	s_barrier
	s_add_i32 s13, s6, s10
	v_readfirstlane_b32 s15, v145
	s_add_i32 s14, s13, 0x100
	s_mov_b32 m0, s15
	v_readfirstlane_b32 s15, v146
	ds_read_b128 v[228:231], v160
	ds_read_b128 v[232:235], v160 offset:1024
	ds_read_b128 v[236:239], v160 offset:2048
	ds_read_b128 v[240:243], v160 offset:3072
	buffer_load_dwordx4 v136, s[28:31], s14 offen lds
	s_mov_b32 m0, s15
	s_add_i32 s11, s11, 2
	buffer_load_dwordx4 v137, s[28:31], s14 offen lds
	s_barrier
	s_waitcnt lgkmcnt(0)
	s_setprio 1
	s_waitcnt lgkmcnt(3)
	v_mfma_f32_16x16x32_bf16 v[30:33], v[228:231], v[184:187], v[30:33]
	s_waitcnt lgkmcnt(1)
	v_mfma_f32_16x16x32_bf16 v[26:29], v[236:239], v[184:187], v[26:29]
	v_mfma_f32_16x16x32_bf16 v[22:25], v[228:231], v[204:207], v[22:25]
	v_mfma_f32_16x16x32_bf16 v[18:21], v[236:239], v[204:207], v[18:21]
	v_mfma_f32_16x16x32_bf16 v[14:17], v[228:231], v[212:215], v[14:17]
	v_mfma_f32_16x16x32_bf16 v[10:13], v[236:239], v[212:215], v[10:13]
	v_mfma_f32_16x16x32_bf16 v[6:9], v[228:231], v[220:223], v[6:9]
	v_mfma_f32_16x16x32_bf16 v[2:5], v[236:239], v[220:223], v[2:5]
	v_mfma_f32_16x16x32_bf16 v[30:33], v[232:235], v[188:191], v[30:33]
	s_waitcnt lgkmcnt(0)
	v_mfma_f32_16x16x32_bf16 v[26:29], v[240:243], v[188:191], v[26:29]
	v_mfma_f32_16x16x32_bf16 v[22:25], v[232:235], v[208:211], v[22:25]
	v_mfma_f32_16x16x32_bf16 v[18:21], v[240:243], v[208:211], v[18:21]
	v_mfma_f32_16x16x32_bf16 v[14:17], v[232:235], v[216:219], v[14:17]
	v_mfma_f32_16x16x32_bf16 v[10:13], v[240:243], v[216:219], v[10:13]
	v_mfma_f32_16x16x32_bf16 v[6:9], v[232:235], v[224:227], v[6:9]
	v_mfma_f32_16x16x32_bf16 v[2:5], v[240:243], v[224:227], v[2:5]
	s_setprio 0
	s_add_i32 s14, s9, s10
	v_readfirstlane_b32 s16, v147
	s_add_i32 s15, s14, 0x100
	s_mov_b32 m0, s16
	v_readfirstlane_b32 s16, v148
	s_barrier
	ds_read_b128 v[184:187], v141 offset:16384
	ds_read_b128 v[188:191], v141 offset:17408
	ds_read_b128 v[204:207], v140 offset:16384
	ds_read_b128 v[208:211], v140 offset:17408
	ds_read_b128 v[212:215], v139 offset:16384
	ds_read_b128 v[216:219], v139 offset:17408
	ds_read_b128 v[220:223], v138 offset:16384
	ds_read_b128 v[224:227], v138 offset:17408
	buffer_load_dwordx4 v143, s[44:47], s15 offen lds
	s_mov_b32 m0, s16
	s_nop 0
	buffer_load_dwordx4 v142, s[44:47], s15 offen lds
	s_barrier
	s_waitcnt lgkmcnt(0)
	s_barrier
	s_add_i32 s15, s8, s10
	v_readfirstlane_b32 s17, v150
	s_add_i32 s16, s15, 0x100
	s_mov_b32 m0, s17
	v_readfirstlane_b32 s17, v151
	buffer_load_dwordx4 v136, s[28:31], s16 offen lds
	s_mov_b32 m0, s17
	s_nop 0
	buffer_load_dwordx4 v137, s[28:31], s16 offen lds
	s_waitcnt vmcnt(6)
	s_barrier
	s_barrier
	ds_read_b128 v[164:167], v149
	ds_read_b128 v[172:175], v149 offset:1024
	ds_read_b128 v[176:179], v149 offset:2048
	ds_read_b128 v[180:183], v149 offset:3072
	v_readfirstlane_b32 s16, v152
	s_addk_i32 s12, 0x100
	s_mov_b32 m0, s16
	v_readfirstlane_b32 s16, v153
	ds_read_b128 v[184:187], v141 offset:32768
	ds_read_b128 v[188:191], v141 offset:33792
	ds_read_b128 v[204:207], v140 offset:32768
	ds_read_b128 v[208:211], v140 offset:33792
	ds_read_b128 v[212:215], v139 offset:32768
	ds_read_b128 v[216:219], v139 offset:33792
	ds_read_b128 v[220:223], v138 offset:32768
	ds_read_b128 v[224:227], v138 offset:33792
	buffer_load_dwordx4 v143, s[44:47], s12 offen lds
	s_mov_b32 m0, s16
	s_nop 0
	buffer_load_dwordx4 v142, s[44:47], s12 offen lds
	s_waitcnt lgkmcnt(8)
	s_barrier
; #define WAIT_V(n) asm volatile("s_waitcnt vmcnt(" #n ")" ::: "memory")
; #define WAIT_L(n) asm volatile("s_waitcnt lgkmcnt(" #n ")" ::: "memory")
; #define BAR __builtin_amdgcn_s_barrier()
; #define SCHED __builtin_amdgcn_sched_barrier(0)
; DEVI void gemm256(const P& p, const u16* A, int lda, const u16* Bt, int ldb, int K, int brow, int bcol, int mode,
;                         int aux, int layer, int bmode) {
;     ...
;     LDB(B0, 1, 0); SCHED; LDA(At, 1, 0); STAGEA(SA(0, 1), brow + HALF, t + 2);
;     WAIT_L(8); BAR; WAIT_L(0); MMA(0, 0, At, B0); BAR; SCHED;
;     LDB(B1, 1, 1); STAGEB(SB(1, 0), bcol, t + 3);
;     BAR; WAIT_L(0); MMA(0, 1, At, B1); BAR;
;     LDA(At, 1, 1); STAGEA(SA(1, 0), brow, t + 3);
;     BAR; WAIT_L(0); MMA(1, 0, At, B0); BAR; SCHED;
;     STAGEB(SB(1, 1), bcol + bhalf, t + 3);
;     WAIT_V(6); BAR; MMA(1, 1, At, B1); BAR;
;   }
;   {
;     LDB(B0, 0, 0); LDA(At, 0, 0); STAGEA(SA(1, 1), brow + HALF, nt - 1);
;     BAR; WAIT_L(0); MMA(0, 0, At, B0); BAR;
	s_waitcnt lgkmcnt(0)
	s_setprio 1
	s_waitcnt lgkmcnt(7)
	v_mfma_f32_16x16x32_bf16 v[126:129], v[164:167], v[184:187], v[126:129]
	v_mfma_f32_16x16x32_bf16 v[122:125], v[176:179], v[184:187], v[122:125]
	s_waitcnt lgkmcnt(5)
	v_mfma_f32_16x16x32_bf16 v[118:121], v[164:167], v[204:207], v[118:121]
	v_mfma_f32_16x16x32_bf16 v[114:117], v[176:179], v[204:207], v[114:117]
	s_waitcnt lgkmcnt(3)
	v_mfma_f32_16x16x32_bf16 v[110:113], v[164:167], v[212:215], v[110:113]
	v_mfma_f32_16x16x32_bf16 v[98:101], v[176:179], v[212:215], v[98:101]
	s_waitcnt lgkmcnt(1)
	v_mfma_f32_16x16x32_bf16 v[82:85], v[164:167], v[220:223], v[82:85]
	v_mfma_f32_16x16x32_bf16 v[62:65], v[176:179], v[220:223], v[62:65]
	v_mfma_f32_16x16x32_bf16 v[126:129], v[172:175], v[188:191], v[126:129]
	v_mfma_f32_16x16x32_bf16 v[122:125], v[180:183], v[188:191], v[122:125]
	v_mfma_f32_16x16x32_bf16 v[118:121], v[172:175], v[208:211], v[118:121]
	v_mfma_f32_16x16x32_bf16 v[114:117], v[180:183], v[208:211], v[114:117]
	v_mfma_f32_16x16x32_bf16 v[110:113], v[172:175], v[216:219], v[110:113]
	v_mfma_f32_16x16x32_bf16 v[98:101], v[180:183], v[216:219], v[98:101]
	s_waitcnt lgkmcnt(0)
	v_mfma_f32_16x16x32_bf16 v[82:85], v[172:175], v[224:227], v[82:85]
	v_mfma_f32_16x16x32_bf16 v[62:65], v[180:183], v[224:227], v[62:65]
	s_setprio 0
	s_barrier
	v_readfirstlane_b32 s12, v154
	s_addk_i32 s13, 0x180
	s_mov_b32 m0, s12
	v_readfirstlane_b32 s12, v155
	ds_read_b128 v[228:231], v144
	ds_read_b128 v[232:235], v144 offset:1024
	ds_read_b128 v[236:239], v144 offset:2048
	ds_read_b128 v[240:243], v144 offset:3072
	buffer_load_dwordx4 v136, s[28:31], s13 offen lds
	s_mov_b32 m0, s12
	s_nop 0
	buffer_load_dwordx4 v137, s[28:31], s13 offen lds
	s_barrier
	s_waitcnt lgkmcnt(0)
	s_setprio 1
	s_waitcnt lgkmcnt(3)
	v_mfma_f32_16x16x32_bf16 v[30:33], v[228:231], v[184:187], v[30:33]
	s_waitcnt lgkmcnt(1)
	v_mfma_f32_16x16x32_bf16 v[26:29], v[236:239], v[184:187], v[26:29]
	v_mfma_f32_16x16x32_bf16 v[22:25], v[228:231], v[204:207], v[22:25]
	v_mfma_f32_16x16x32_bf16 v[18:21], v[236:239], v[204:207], v[18:21]
	v_mfma_f32_16x16x32_bf16 v[14:17], v[228:231], v[212:215], v[14:17]
	v_mfma_f32_16x16x32_bf16 v[10:13], v[236:239], v[212:215], v[10:13]
	v_mfma_f32_16x16x32_bf16 v[6:9], v[228:231], v[220:223], v[6:9]
	v_mfma_f32_16x16x32_bf16 v[2:5], v[236:239], v[220:223], v[2:5]
	v_mfma_f32_16x16x32_bf16 v[30:33], v[232:235], v[188:191], v[30:33]
	s_waitcnt lgkmcnt(0)
	v_mfma_f32_16x16x32_bf16 v[26:29], v[240:243], v[188:191], v[26:29]
	v_mfma_f32_16x16x32_bf16 v[22:25], v[232:235], v[208:211], v[22:25]
	v_mfma_f32_16x16x32_bf16 v[18:21], v[240:243], v[208:211], v[18:21]
	v_mfma_f32_16x16x32_bf16 v[14:17], v[232:235], v[216:219], v[14:17]
	v_mfma_f32_16x16x32_bf16 v[10:13], v[240:243], v[216:219], v[10:13]
	v_mfma_f32_16x16x32_bf16 v[6:9], v[232:235], v[224:227], v[6:9]
	v_mfma_f32_16x16x32_bf16 v[2:5], v[240:243], v[224:227], v[2:5]
	s_setprio 0
	v_readfirstlane_b32 s12, v156
	s_addk_i32 s14, 0x180
	s_mov_b32 m0, s12
	v_readfirstlane_b32 s12, v157
	s_barrier
	ds_read_b128 v[184:187], v141 offset:49152
	ds_read_b128 v[188:191], v141 offset:50176
	ds_read_b128 v[204:207], v140 offset:49152
	ds_read_b128 v[208:211], v140 offset:50176
	ds_read_b128 v[212:215], v139 offset:49152
	ds_read_b128 v[216:219], v139 offset:50176
	ds_read_b128 v[220:223], v138 offset:49152
	ds_read_b128 v[224:227], v138 offset:50176
	buffer_load_dwordx4 v143, s[44:47], s14 offen lds
	s_mov_b32 m0, s12
	s_nop 0
	buffer_load_dwordx4 v142, s[44:47], s14 offen lds
	s_barrier
	s_waitcnt lgkmcnt(0)
	s_barrier
	v_readfirstlane_b32 s12, v161
	s_addk_i32 s15, 0x180
	s_mov_b32 m0, s12
	v_readfirstlane_b32 s12, v162
	buffer_load_dwordx4 v136, s[28:31], s15 offen lds
	s_mov_b32 m0, s12
	s_nop 0
	buffer_load_dwordx4 v137, s[28:31], s15 offen lds
	s_waitcnt vmcnt(6)
	s_barrier
	s_addk_i32 s10, 0x100
	s_cmp_lt_u32 s11, s2
	s_barrier
	s_cbranch_scc1 .Lhm_192
	s_add_i32 s2, s5, s7
	s_lshl_b32 s2, s2, 1
	v_readfirstlane_b32 s3, v159
	s_addk_i32 s2, 0xff80
	s_mov_b32 s46, s30
	s_mov_b32 s47, s31
	s_mov_b32 m0, s3
	v_readfirstlane_b32 s3, v158
	ds_read_b128 v[150:153], v163
	ds_read_b128 v[154:157], v163 offset:1024
	ds_read_b128 v[164:167], v163 offset:2048
	ds_read_b128 v[172:175], v163 offset:3072
	ds_read_b128 v[176:179], v141
	ds_read_b128 v[180:183], v141 offset:1024
	ds_read_b128 v[184:187], v140
	ds_read_b128 v[188:191], v140 offset:1024
	ds_read_b128 v[204:207], v139
	ds_read_b128 v[208:211], v139 offset:1024
	ds_read_b128 v[212:215], v138
	ds_read_b128 v[216:219], v138 offset:1024
	buffer_load_dwordx4 v143, s[44:47], s2 offen lds
	s_mov_b32 m0, s3
	s_nop 0
	buffer_load_dwordx4 v142, s[44:47], s2 offen lds
	s_barrier
	s_waitcnt lgkmcnt(0)
	s_setprio 1
	s_waitcnt lgkmcnt(7)
	v_mfma_f32_16x16x32_bf16 v[126:129], v[150:153], v[176:179], v[126:129]
	v_mfma_f32_16x16x32_bf16 v[122:125], v[164:167], v[176:179], v[122:125]
	s_waitcnt lgkmcnt(5)
	v_mfma_f32_16x16x32_bf16 v[118:121], v[150:153], v[184:187], v[118:121]
	v_mfma_f32_16x16x32_bf16 v[114:117], v[164:167], v[184:187], v[114:117]
	s_waitcnt lgkmcnt(3)
	v_mfma_f32_16x16x32_bf16 v[110:113], v[150:153], v[204:207], v[110:113]
	v_mfma_f32_16x16x32_bf16 v[98:101], v[164:167], v[204:207], v[98:101]
	s_waitcnt lgkmcnt(1)
	v_mfma_f32_16x16x32_bf16 v[82:85], v[150:153], v[212:215], v[82:85]
	v_mfma_f32_16x16x32_bf16 v[62:65], v[164:167], v[212:215], v[62:65]
	v_mfma_f32_16x16x32_bf16 v[126:129], v[154:157], v[180:183], v[126:129]
	v_mfma_f32_16x16x32_bf16 v[122:125], v[172:175], v[180:183], v[122:125]
	v_mfma_f32_16x16x32_bf16 v[118:121], v[154:157], v[188:191], v[118:121]
	v_mfma_f32_16x16x32_bf16 v[114:117], v[172:175], v[188:191], v[114:117]
	v_mfma_f32_16x16x32_bf16 v[110:113], v[154:157], v[208:211], v[110:113]
	v_mfma_f32_16x16x32_bf16 v[98:101], v[172:175], v[208:211], v[98:101]
	s_waitcnt lgkmcnt(0)
	v_mfma_f32_16x16x32_bf16 v[82:85], v[154:157], v[216:219], v[82:85]
	v_mfma_f32_16x16x32_bf16 v[62:65], v[172:175], v[216:219], v[62:65]
	s_setprio 0
	s_barrier
; #define WAIT_V(n) asm volatile("s_waitcnt vmcnt(" #n ")" ::: "memory")
; #define WAIT_L(n) asm volatile("s_waitcnt lgkmcnt(" #n ")" ::: "memory")
; #define BAR __builtin_amdgcn_s_barrier()
; DEVI void gemm256(const P& p, const u16* A, int lda, const u16* Bt, int ldb, int K, int brow, int bcol, int mode,
;                         int aux, int layer, int bmode) {
;     ...
;     LDB(B1, 0, 1); BAR; WAIT_L(0); MMA(0, 1, At, B1); BAR;
;     LDA(At, 0, 1); WAIT_V(4); BAR; WAIT_L(0); MMA(1, 0, At, B0); MMA(1, 1, At, B1); BAR;
;   }
;   {
;     LDB(B0, 1, 0); LDA(At, 1, 0); WAIT_V(2); BAR; WAIT_L(0); MMA(0, 0, At, B0); BAR;
;     LDB(B1, 1, 1); WAIT_V(0); BAR; WAIT_L(0); MMA(0, 1, At, B1); BAR;
;     LDA(At, 1, 1); BAR; WAIT_L(0); MMA(1, 0, At, B0); MMA(1, 1, At, B1); BAR;
;   }
;   if (wr == 0) BAR;
	ds_read_b128 v[220:223], v160
	ds_read_b128 v[224:227], v160 offset:1024
	ds_read_b128 v[228:231], v160 offset:2048
	ds_read_b128 v[158:161], v160 offset:3072
	s_barrier
	s_waitcnt lgkmcnt(0)
	s_setprio 1
	s_waitcnt lgkmcnt(3)
	v_mfma_f32_16x16x32_bf16 v[30:33], v[220:223], v[176:179], v[30:33]
	s_waitcnt lgkmcnt(1)
	v_mfma_f32_16x16x32_bf16 v[26:29], v[228:231], v[176:179], v[26:29]
	v_mfma_f32_16x16x32_bf16 v[22:25], v[220:223], v[184:187], v[22:25]
	v_mfma_f32_16x16x32_bf16 v[18:21], v[228:231], v[184:187], v[18:21]
	v_mfma_f32_16x16x32_bf16 v[14:17], v[220:223], v[204:207], v[14:17]
	v_mfma_f32_16x16x32_bf16 v[10:13], v[228:231], v[204:207], v[10:13]
	v_mfma_f32_16x16x32_bf16 v[6:9], v[220:223], v[212:215], v[6:9]
	v_mfma_f32_16x16x32_bf16 v[2:5], v[228:231], v[212:215], v[2:5]
	v_mfma_f32_16x16x32_bf16 v[30:33], v[224:227], v[180:183], v[30:33]
	s_waitcnt lgkmcnt(0)
	v_mfma_f32_16x16x32_bf16 v[26:29], v[158:161], v[180:183], v[26:29]
	v_mfma_f32_16x16x32_bf16 v[22:25], v[224:227], v[188:191], v[22:25]
	v_mfma_f32_16x16x32_bf16 v[18:21], v[158:161], v[188:191], v[18:21]
	v_mfma_f32_16x16x32_bf16 v[14:17], v[224:227], v[208:211], v[14:17]
	v_mfma_f32_16x16x32_bf16 v[10:13], v[158:161], v[208:211], v[10:13]
	v_mfma_f32_16x16x32_bf16 v[6:9], v[224:227], v[216:219], v[6:9]
	v_mfma_f32_16x16x32_bf16 v[2:5], v[158:161], v[216:219], v[2:5]
	s_setprio 0
	s_barrier
	ds_read_b128 v[176:179], v141 offset:16384
	ds_read_b128 v[180:183], v141 offset:17408
	ds_read_b128 v[184:187], v140 offset:16384
	ds_read_b128 v[188:191], v140 offset:17408
	ds_read_b128 v[204:207], v139 offset:16384
	ds_read_b128 v[208:211], v139 offset:17408
	ds_read_b128 v[212:215], v138 offset:16384
	ds_read_b128 v[216:219], v138 offset:17408
	s_waitcnt vmcnt(4)
	s_barrier
	s_waitcnt lgkmcnt(0)
	s_barrier
	ds_read_b128 v[204:207], v149
	ds_read_b128 v[208:211], v149 offset:1024
	ds_read_b128 v[212:215], v149 offset:2048
	ds_read_b128 v[146:149], v149 offset:3072
	s_nop 0
	ds_read_b128 v[50:53], v141 offset:32768
	ds_read_b128 v[54:57], v141 offset:33792
	ds_read_b128 v[58:61], v140 offset:32768
	ds_read_b128 v[66:69], v140 offset:33792
	ds_read_b128 v[70:73], v139 offset:32768
	ds_read_b128 v[78:81], v139 offset:33792
	ds_read_b128 v[216:219], v138 offset:32768
	ds_read_b128 v[220:223], v138 offset:33792
	s_waitcnt vmcnt(2)
	s_barrier
	s_waitcnt lgkmcnt(0)
	s_setprio 1
	s_waitcnt lgkmcnt(7)
	v_mfma_f32_16x16x32_bf16 v[74:77], v[204:207], v[50:53], v[126:129]
	s_waitcnt lgkmcnt(6)
	v_mfma_f32_16x16x32_bf16 v[126:129], v[208:211], v[54:57], v[74:77]
	v_mfma_f32_16x16x32_bf16 v[74:77], v[212:215], v[50:53], v[122:125]
	v_mfma_f32_16x16x32_bf16 v[122:125], v[146:149], v[54:57], v[74:77]
	s_waitcnt lgkmcnt(5)
	v_mfma_f32_16x16x32_bf16 v[74:77], v[204:207], v[58:61], v[118:121]
	s_waitcnt lgkmcnt(4)
	v_mfma_f32_16x16x32_bf16 v[118:121], v[208:211], v[66:69], v[74:77]
	v_mfma_f32_16x16x32_bf16 v[74:77], v[212:215], v[58:61], v[114:117]
	v_mfma_f32_16x16x32_bf16 v[114:117], v[146:149], v[66:69], v[74:77]
	s_waitcnt lgkmcnt(3)
	v_mfma_f32_16x16x32_bf16 v[74:77], v[204:207], v[70:73], v[110:113]
	s_waitcnt lgkmcnt(2)
	v_mfma_f32_16x16x32_bf16 v[110:113], v[208:211], v[78:81], v[74:77]
	v_mfma_f32_16x16x32_bf16 v[74:77], v[212:215], v[70:73], v[98:101]
	v_mfma_f32_16x16x32_bf16 v[102:105], v[146:149], v[78:81], v[74:77]
	s_waitcnt lgkmcnt(1)
	v_mfma_f32_16x16x32_bf16 v[74:77], v[204:207], v[216:219], v[82:85]
	v_mfma_f32_16x16x32_bf16 v[62:65], v[212:215], v[216:219], v[62:65]
	s_waitcnt lgkmcnt(0)
	v_mfma_f32_16x16x32_bf16 v[98:101], v[208:211], v[220:223], v[74:77]
	v_mfma_f32_16x16x32_bf16 v[90:93], v[146:149], v[220:223], v[62:65]
	s_setprio 0
	s_barrier
	ds_read_b128 v[224:227], v144
	ds_read_b128 v[228:231], v144 offset:1024
	ds_read_b128 v[240:243], v144 offset:2048
	ds_read_b128 v[142:145], v144 offset:3072
	s_waitcnt vmcnt(0)
	s_barrier
	s_waitcnt lgkmcnt(0)
	s_setprio 1
	s_waitcnt lgkmcnt(3)
	v_mfma_f32_16x16x32_bf16 v[30:33], v[224:227], v[50:53], v[30:33]
	s_waitcnt lgkmcnt(1)
	v_mfma_f32_16x16x32_bf16 v[26:29], v[240:243], v[50:53], v[26:29]
	v_mfma_f32_16x16x32_bf16 v[22:25], v[224:227], v[58:61], v[22:25]
	v_mfma_f32_16x16x32_bf16 v[18:21], v[240:243], v[58:61], v[18:21]
	v_mfma_f32_16x16x32_bf16 v[14:17], v[224:227], v[70:73], v[14:17]
	v_mfma_f32_16x16x32_bf16 v[10:13], v[240:243], v[70:73], v[10:13]
	v_mfma_f32_16x16x32_bf16 v[6:9], v[224:227], v[216:219], v[6:9]
	v_mfma_f32_16x16x32_bf16 v[2:5], v[240:243], v[216:219], v[2:5]
	v_mfma_f32_16x16x32_bf16 v[106:109], v[228:231], v[54:57], v[30:33]
	s_waitcnt lgkmcnt(0)
	v_mfma_f32_16x16x32_bf16 v[94:97], v[142:145], v[54:57], v[26:29]
	v_mfma_f32_16x16x32_bf16 v[86:89], v[228:231], v[66:69], v[22:25]
	v_mfma_f32_16x16x32_bf16 v[82:85], v[142:145], v[66:69], v[18:21]
	v_mfma_f32_16x16x32_bf16 v[74:77], v[228:231], v[78:81], v[14:17]
	v_mfma_f32_16x16x32_bf16 v[66:69], v[142:145], v[78:81], v[10:13]
	v_mfma_f32_16x16x32_bf16 v[62:65], v[228:231], v[220:223], v[6:9]
	v_mfma_f32_16x16x32_bf16 v[54:57], v[142:145], v[220:223], v[2:5]
	s_setprio 0
	s_barrier
	s_nop 0
	ds_read_b128 v[2:5], v141 offset:49152
	ds_read_b128 v[6:9], v141 offset:50176
	ds_read_b128 v[10:13], v140 offset:49152
	ds_read_b128 v[14:17], v140 offset:50176
	ds_read_b128 v[216:219], v139 offset:49152
	ds_read_b128 v[220:223], v139 offset:50176
	ds_read_b128 v[244:247], v138 offset:49152
	ds_read_b128 v[136:139], v138 offset:50176
	s_barrier
	s_waitcnt lgkmcnt(0)
.Lhm_join:
	s_movk_i32 s2, 0x100
	v_cmp_gt_u32_e32 vcc, s2, v130
	s_barrier
	s_and_saveexec_b64 s[2:3], vcc
	s_cbranch_execz .LBB0_195
	s_barrier
; #define opqp(x) ((x) + opqz())
; #define LDS_BAR() do { asm volatile("s_waitcnt lgkmcnt(0)" ::: "memory"); __builtin_amdgcn_s_barrier(); asm volatile("" ::: "memory"); } while (0)
; DEVI void gemm256(const P& p, const u16* A, int lda, const u16* Bt, int ldb, int K, int brow, int bcol, int mode,
;                         int aux, int layer, int bmode) {
;     ...
;   char* ws = opqp(p.ws);
;   const int bb = brow / TPB;
;   const int trow = brow - bb * TPB;
;   u16* stg = (u16*)shm;
;   const int tid = TIDX;
;     ...
; #pragma unroll
;   for (int ai = 0; ai < 2; ++ai)
; #pragma unroll
;     for (int bj = 0; bj < (G8 ? 2 : 1); ++bj)
; #pragma unroll
;       for (int m = 0; m < 4; ++m)
; #pragma unroll
;         for (int n = 0; n < 2; ++n) {
;           const int R = ai * HALF + wr * 64 + m * 16 + fr;
;           const int chunk = bj * 16 + wc * 4 + n * 2 + (fq >> 1);
;           f32x4 v = acc[ai][bj][m][n];
;           uint2 pk = make_uint2(pk2(v[0], v[1]), pk2(v[2], v[3]));
;           *(uint2*)(stg + R * 256 + SWZ(R, chunk) * 8 + (fq & 1) * 4) = pk;
;         }
;   LDS_BAR();
.LBB0_195:
	s_or_b64 exec, exec, s[2:3]
	v_lshrrev_b32_e32 v134, 1, v134
	v_lshlrev_b32_e32 v133, 3, v133
	v_lshlrev_b32_e32 v136, 4, v134
	v_and_b32_e32 v133, 8, v133
	v_or_b32_e32 v134, v134, v135
	v_add_u32_e32 v133, 16, v133
	v_lshlrev_b32_e32 v132, 15, v132
	v_lshlrev_b32_e32 v135, 9, v131
	v_cvt_pk_bf16_f32 v126, v126, v127
	v_cvt_pk_bf16_f32 v127, v128, v129
	v_bitop3_b32 v128, v136, v134, v131 bitop3:0x36
	v_add3_u32 v132, v133, v132, v135
	v_lshlrev_b32_e32 v128, 4, v128
	v_cvt_pk_bf16_f32 v90, v90, v91
	v_cvt_pk_bf16_f32 v91, v92, v93
	v_or_b32_e32 v92, 16, v134
	s_mov_b64 s[28:29], 0
	v_add_u32_e32 v129, v132, v128
	v_cvt_pk_bf16_f32 v110, v110, v111
	v_cvt_pk_bf16_f32 v111, v112, v113
	v_cvt_pk_bf16_f32 v98, v98, v99
	v_cvt_pk_bf16_f32 v99, v100, v101
	v_bitop3_b32 v92, v136, v92, v131 bitop3:0x36
	v_or_b32_e32 v100, 18, v134
	s_waitcnt vmcnt(0)
	ds_write2st64_b64 v129, v[110:111], v[98:99] offset0:32 offset1:48
	v_lshlrev_b32_e32 v98, 4, v92
	v_cvt_pk_bf16_f32 v92, v94, v95
	v_bitop3_b32 v94, v136, v100, v131 bitop3:0x36
	v_or_b32_e32 v133, 2, v134
	v_lshlrev_b32_e32 v94, 4, v94
	v_cvt_pk_bf16_f32 v122, v122, v123
	v_cvt_pk_bf16_f32 v123, v124, v125
	v_bitop3_b32 v124, v136, v133, v131 bitop3:0x36
	v_add_u32_e32 v95, v132, v94
	v_cvt_pk_bf16_f32 v66, v66, v67
	v_cvt_pk_bf16_f32 v67, v68, v69
	v_cvt_pk_bf16_f32 v54, v54, v55
	v_cvt_pk_bf16_f32 v55, v56, v57
	v_add_u32_e32 v56, 0x10000, v132
	v_lshlrev_b32_e32 v124, 4, v124
	ds_write2st64_b64 v95, v[66:67], v[54:55] offset0:32 offset1:48
	v_cvt_pk_bf16_f32 v54, v78, v79
	v_cvt_pk_bf16_f32 v55, v80, v81
	v_add_u32_e32 v57, v56, v128
	ds_write_b64 v57, v[54:55]
	v_cvt_pk_bf16_f32 v54, v70, v71
	v_cvt_pk_bf16_f32 v55, v72, v73
	v_add_u32_e32 v57, v56, v124
	ds_write_b64 v57, v[54:55]
	v_add_u32_e32 v57, 0x12000, v132
	v_cvt_pk_bf16_f32 v50, v50, v51
	v_cvt_pk_bf16_f32 v51, v52, v53
	v_add_u32_e32 v52, v57, v124
	ds_write_b64 v52, v[50:51]
	v_add_u32_e32 v50, 0x14000, v132
	v_cvt_pk_bf16_f32 v42, v42, v43
	v_cvt_pk_bf16_f32 v43, v44, v45
	v_add_u32_e32 v44, v50, v124
	v_add_u32_e32 v125, v132, v124
	v_cvt_pk_bf16_f32 v102, v102, v103
	v_cvt_pk_bf16_f32 v103, v104, v105
	ds_write_b64 v44, v[42:43]
	v_add_u32_e32 v42, 0x16000, v132
	v_cvt_pk_bf16_f32 v118, v118, v119
	v_cvt_pk_bf16_f32 v119, v120, v121
	v_cvt_pk_bf16_f32 v114, v114, v115
	v_cvt_pk_bf16_f32 v115, v116, v117
	ds_write2st64_b64 v125, v[102:103], v[90:91] offset0:32 offset1:48
	v_cvt_pk_bf16_f32 v90, v106, v107
	v_cvt_pk_bf16_f32 v91, v108, v109
	v_add_u32_e32 v99, v132, v98
	v_cvt_pk_bf16_f32 v93, v96, v97
	v_cvt_pk_bf16_f32 v86, v86, v87
	v_cvt_pk_bf16_f32 v87, v88, v89
	v_cvt_pk_bf16_f32 v82, v82, v83
	v_cvt_pk_bf16_f32 v83, v84, v85
	v_cvt_pk_bf16_f32 v74, v74, v75
	v_cvt_pk_bf16_f32 v75, v76, v77
	v_cvt_pk_bf16_f32 v62, v62, v63
	v_cvt_pk_bf16_f32 v63, v64, v65
	v_cvt_pk_bf16_f32 v54, v58, v59
	v_cvt_pk_bf16_f32 v55, v60, v61
	v_add_u32_e32 v58, v57, v128
	v_cvt_pk_bf16_f32 v46, v46, v47
	v_cvt_pk_bf16_f32 v47, v48, v49
	v_add_u32_e32 v48, v50, v128
	v_cvt_pk_bf16_f32 v38, v38, v39
	v_cvt_pk_bf16_f32 v39, v40, v41
	v_add_u32_e32 v40, v42, v128
	v_cvt_pk_bf16_f32 v34, v34, v35
	v_cvt_pk_bf16_f32 v35, v36, v37
	v_add_u32_e32 v36, v42, v124
	v_cvt_pk_bf16_f32 v30, v30, v31
	v_cvt_pk_bf16_f32 v31, v32, v33
	v_add_u32_e32 v32, v56, v98
	v_cvt_pk_bf16_f32 v26, v26, v27
	v_cvt_pk_bf16_f32 v27, v28, v29
	v_add_u32_e32 v28, v56, v94
	v_cvt_pk_bf16_f32 v22, v22, v23
	v_cvt_pk_bf16_f32 v23, v24, v25
	v_add_u32_e32 v24, v57, v98
	v_cvt_pk_bf16_f32 v18, v18, v19
	v_cvt_pk_bf16_f32 v19, v20, v21
	v_add_u32_e32 v20, v57, v94
	v_cvt_pk_bf16_f32 v14, v14, v15
	v_cvt_pk_bf16_f32 v15, v16, v17
	v_add_u32_e32 v16, v50, v98
	v_cvt_pk_bf16_f32 v10, v10, v11
	v_cvt_pk_bf16_f32 v11, v12, v13
	v_add_u32_e32 v12, v50, v94
	v_cvt_pk_bf16_f32 v6, v6, v7
	v_cvt_pk_bf16_f32 v7, v8, v9
	v_add_u32_e32 v8, v42, v98
	v_cvt_pk_bf16_f32 v2, v2, v3
	v_cvt_pk_bf16_f32 v3, v4, v5
	v_add_u32_e32 v4, v42, v94
	ds_write2st64_b64 v129, v[126:127], v[118:119] offset1:16
	ds_write2st64_b64 v125, v[122:123], v[114:115] offset1:16
	ds_write2st64_b64 v99, v[90:91], v[86:87] offset1:16
	ds_write2st64_b64 v95, v[92:93], v[82:83] offset1:16
	ds_write2st64_b64 v99, v[74:75], v[62:63] offset0:32 offset1:48
	ds_write_b64 v58, v[54:55]
	ds_write_b64 v48, v[46:47]
	ds_write_b64 v40, v[38:39]
	ds_write_b64 v36, v[34:35]
	ds_write_b64 v32, v[30:31]
	ds_write_b64 v28, v[26:27]
	ds_write_b64 v24, v[22:23]
	ds_write_b64 v20, v[18:19]
	ds_write_b64 v16, v[14:15]
	ds_write_b64 v12, v[10:11]
	ds_write_b64 v8, v[6:7]
	ds_write_b64 v4, v[2:3]
	s_waitcnt lgkmcnt(0)
	s_barrier
	s_mov_b64 s[2:3], -1
	s_and_b64 vcc, exec, s[36:37]
	v_and_b32_e32 v64, 16, v0
	v_readlane_b32 s26, v251, 10
	s_cbranch_vccz .LBB0_313
; DEVI float silu_f(float x) { return x / (1.f + __expf(-x)); }
; DEVI void gemm256(const P& p, const u16* A, int lda, const u16* Bt, int ldb, int K, int brow, int bcol, int mode,
;                         int aux, int layer, int bmode) {
;     ...
;   } else {
;     bool tr0 = false, tr1 = false;
;     if (mode == M_G1A) { tr0 = bcol >= C_AV && bcol < C_AG; tr1 = bcol + HALF >= C_AV && bcol + HALF < C_AG; }
;     else if (mode == M_G3) { tr1 = true; }
; #pragma unroll 4
;     for (int it = 0; it < 16; ++it) {
;       const int R = it * 16 + (tid >> 5), c = tid & 31;
;       if ((c < 16) ? tr0 : tr1) continue;
;       const int row = brow + R, col = bcol + c * 8;
;       bf16x8 raw = *(const bf16x8*)(stg + R * 256 + SWZ(R, c) * 8);
;       if (mode == M_G1A) {
;         *(bf16x8*)((u16*)(ws + O_PROJ) + (size_t)row * NP + col) = raw;
;       } else if (mode == M_G4) {
;         *(bf16x8*)((u16*)(ws + O_YBR) + (size_t)row * 8192 + aux * 2048 + col) = raw;
;       } else {
;         float v[8];
; #pragma unroll
;         for (int e = 0; e < 8; ++e) v[e] = bfs(raw[e]);
;         if (mode == M_G2) {
;           float rs = ((const float*)(ws + O_RINV))[row * 2];
; #pragma unroll
;           for (int e = 0; e < 8; ++e) v[e] *= rs;
;           st8((u16*)(ws + O_QH) + (size_t)row * 768 + col, v);
;         } else if (mode == M_G3) {
;           float rs = ((const float*)(ws + O_RINV))[row * 2 + 1];
; #pragma unroll
;           for (int e = 0; e < 8; ++e) v[e] *= rs;
;           st8((u16*)(ws + O_KH) + ((size_t)(bb * 4 + (col >> 8)) * TPB + (trow + R)) * 192 + (col & 255), v);
;         } else if (mode == M_POOL) {
;           float g[8];
;           ld8((const u16*)(ws + O_PROJ) + (size_t)row * NP + C_BG + col, g);
; #pragma unroll
;           for (int e = 0; e < 8; ++e) {
;             float y = bf2f(f2bf(v[e] * p.pool_scale[layer * 512 + col + e]));
;             v[e] = y * silu_f(g[e]);
;           }
;           st8((u16*)(ws + O_YS) + (size_t)row * 2048 + 512 + col, v);
;         } else {
;           float* xb;
;           const float* gv;
;           const float* xs;
;           if (trow == 0) {
;             xb = (float*)(ws + O_XC) + ((size_t)bb * CTXL + R) * D + col;
;             xs = (layer == 0) ? p.ctx + ((size_t)bb * CTXL + R) * D + col : xb;
;             gv = (const float*)(ws + O_MOD) + ((size_t)layer * 5 + 4) * 6144 + 4096 + col;
;           } else {
	v_readlane_b32 s60, v249, 42
	v_readlane_b32 s64, v249, 46
	v_readlane_b32 s2, v249, 53
	s_mul_i32 s47, s72, 0xffffef00
	v_readlane_b32 s65, v249, 47
	s_add_u32 s80, s64, s28
	s_addc_u32 s81, s65, s29
	s_add_i32 s46, s47, s70
	s_and_b32 s2, s97, 0xfffffe00
	v_readlane_b32 s3, v249, 54
	s_cmpk_eq_i32 s2, 0x400
	s_cselect_b64 s[2:3], -1, 0
	s_add_i32 s5, s97, 0xfffffc80
	s_cmpk_lt_u32 s5, 0x200
	s_cselect_b64 s[6:7], -1, 0
	v_cndmask_b32_e64 v0, 0, 1, s[6:7]
	v_cndmask_b32_e64 v2, 0, 1, s[68:69]
	v_and_b32_e32 v3, 31, v130
	s_and_b64 s[2:3], s[38:39], s[2:3]
	v_cndmask_b32_e64 v0, v2, v0, s[38:39]
	v_cndmask_b32_e64 v65, 0, 1, s[2:3]
	v_cmp_gt_u32_e32 vcc, 16, v3
	v_and_b32_e32 v2, 1, v0
	v_ashrrev_i32_e32 v10, 5, v130
	v_cndmask_b32_e32 v0, v0, v65, vcc
	v_and_b32_e32 v0, 1, v0
	v_cmp_eq_u32_e32 vcc, 1, v0
	v_and_b32_e32 v0, 15, v10
	v_cmp_eq_u32_e64 s[44:45], 1, v2
	v_lshl_add_u32 v2, v3, 3, s97
	v_bitop3_b32 v0, v0, v3, v64 bitop3:0x36
	v_lshlrev_b32_e32 v8, 4, v0
	v_readlane_b32 s2, v248, 15
	v_ashrrev_i32_e32 v0, 8, v2
	s_xor_b64 s[82:83], vcc, -1
	v_add_u32_e32 v4, s2, v2
	v_lshl_add_u32 v0, s72, 2, v0
	s_movk_i32 s2, 0x1100
	s_mov_b64 s[88:89], s[84:85]
	v_mad_i64_i32 v[12:13], s[2:3], v0, s2, 0
	v_and_b32_e32 v0, 0xf8, v2
	s_add_u32 s84, s80, 0x2221a000
	v_ashrrev_i32_e32 v3, 31, v2
	v_lshlrev_b32_e32 v0, 1, v0
	s_addc_u32 s85, s81, 0
	v_lshl_add_u64 v[6:7], s[80:81], 0, v[0:1]
	s_mov_b64 s[2:3], 0x1b28a000
	v_lshlrev_b64 v[16:17], 1, v[2:3]
	s_cmp_lg_u32 s46, 0
	v_lshl_add_u64 v[14:15], v[6:7], 0, s[2:3]
	v_lshl_add_u64 v[6:7], s[80:81], 0, v[16:17]
	s_mov_b64 s[2:3], 0x1990a000
	s_cselect_b64 s[54:55], -1, 0
	s_ashr_i32 s73, s72, 31
	s_add_i32 s5, s46, 0xffffff00
	v_lshl_add_u64 v[18:19], v[6:7], 0, s[2:3]
	s_lshl_b64 s[2:3], s[72:73], 12
	s_ashr_i32 s6, s5, 31
	s_add_u32 s56, s2, s5
	v_readlane_b32 s2, v248, 16
	s_addc_u32 s57, s3, s6
	s_add_i32 s2, s2, s72
	s_mul_hi_i32 s3, s2, 0x6000
	s_mulk_i32 s2, 0x6000
	s_add_u32 s2, s80, s2
	s_addc_u32 s3, s81, s3
	s_add_u32 s58, s2, 0x5614000
	s_addc_u32 s59, s3, 0
	s_lshl_b64 s[2:3], s[72:73], 19
	v_writelane_b32 v248, s2, 20
	v_lshlrev_b64 v[20:21], 2, v[2:3]
	v_lshl_add_u64 v[2:3], s[80:81], 0, v[20:21]
	v_writelane_b32 v248, s3, 21
	s_mov_b64 s[2:3], 0x568a000
	v_lshl_add_u64 v[22:23], v[2:3], 0, s[2:3]
	v_readlane_b32 s2, v248, 17
	s_add_u32 s2, s80, s2
	s_addc_u32 s3, s81, 0
	v_readlane_b32 s61, v249, 43
	s_add_u32 s60, s2, 0x562c000
	s_addc_u32 s61, s3, 0
	s_add_u32 s2, s80, 0xa28a000
	v_readlane_b32 s8, v251, 11
	s_addc_u32 s3, s81, 0
	s_lshl_b64 s[6:7], s[34:35], 1
	v_ashrrev_i32_e32 v5, 31, v4
	v_readlane_b32 s9, v251, 12
	v_readlane_b32 s10, v251, 13
	v_readlane_b32 s11, v251, 14
	v_readlane_b32 s12, v251, 15
	v_readlane_b32 s13, v251, 16
	v_readlane_b32 s14, v251, 17
	v_readlane_b32 s15, v251, 18
	v_readlane_b32 s16, v251, 19
	v_readlane_b32 s17, v251, 20
	v_readlane_b32 s18, v251, 21
	v_readlane_b32 s19, v251, 22
	v_readlane_b32 s20, v251, 23
	v_readlane_b32 s21, v251, 24
	v_readlane_b32 s22, v251, 25
	v_readlane_b32 s23, v251, 26
	s_add_u32 s6, s2, s6
	v_lshl_add_u64 v[30:31], v[4:5], 2, s[12:13]
	v_readlane_b32 s8, v249, 26
	s_addc_u32 s7, s3, s7
	v_lshl_add_u64 v[26:27], s[2:3], 0, v[16:17]
	s_lshl_b64 s[2:3], s[72:73], 21
	v_readlane_b32 s12, v249, 30
	v_lshl_add_u64 v[24:25], s[6:7], 0, v[16:17]
	v_readlane_b32 s13, v249, 31
	s_add_u32 s6, s12, s2
	s_addc_u32 s7, s13, s3
	v_ashrrev_i32_e32 v11, 31, v10
	s_add_u32 s2, s28, s2
	v_lshlrev_b64 v[2:3], 13, v[10:11]
	s_addc_u32 s3, s29, s3
	v_lshl_add_u64 v[32:33], s[6:7], 0, v[2:3]
	v_lshl_add_u64 v[2:3], s[2:3], 0, v[2:3]
	v_lshl_add_u64 v[2:3], v[2:3], 0, v[20:21]
	v_lshl_add_u64 v[34:35], s[64:65], 0, v[2:3]
	v_lshl_add_u64 v[2:3], s[56:57], 0, v[10:11]
	v_readlane_b32 s9, v249, 27
	v_lshlrev_b64 v[2:3], 13, v[2:3]
	v_readlane_b32 s62, v249, 44
	v_readlane_b32 s63, v249, 45
	v_readlane_b32 s66, v249, 48
	v_readlane_b32 s67, v249, 49
	v_readlane_b32 s20, v249, 38
	v_lshl_or_b32 v0, v10, 9, v8
	v_lshl_add_u64 v[40:41], s[8:9], 0, v[2:3]
	v_lshl_add_u64 v[2:3], v[2:3], 0, v[20:21]
	s_mov_b32 s50, 0
	v_lshl_add_u64 v[28:29], s[62:63], 0, v[20:21]
	v_add_u32_e32 v36, s70, v10
	v_add_u32_e32 v0, 16, v0
	v_lshl_add_u32 v38, v10, 1, s4
	v_lshl_add_u64 v[42:43], s[62:63], 0, v[2:3]
	s_mov_b64 s[66:67], 0
	s_movk_i32 s20, 0x600
	v_readlane_b32 s10, v249, 28
	v_readlane_b32 s11, v249, 29
	v_readlane_b32 s14, v249, 32
	v_readlane_b32 s15, v249, 33
	v_readlane_b32 s16, v249, 34
	v_readlane_b32 s17, v249, 35
	v_readlane_b32 s18, v249, 36
	v_readlane_b32 s19, v249, 37
	v_readlane_b32 s21, v249, 39
	v_readlane_b32 s22, v249, 40
	v_readlane_b32 s23, v249, 41
	s_cmp_lg_u32 s71, 6
	s_cbranch_scc1 .LBB0_198
	s_cmp_lg_u32 s98, 0
	s_cbranch_scc1 .Lg5_half
	s_mov_b64 s[4:5], 0x20000
	s_and_b64 vcc, exec, s[54:55]
	s_cbranch_vccz .Lg5_ctx
	v_lshl_add_u64 v[52:53], v[40:41], 0, v[20:21]
	v_mov_b32_e32 v54, v42
	v_mov_b32_e32 v55, v43
	s_mov_b64 s[2:3], s[58:59]
	s_branch .Lg5_common

; DEVI void gemm256(const P& p, const u16* A, int lda, const u16* Bt, int ldb, int K, int brow, int bcol, int mode,
;                         int aux, int layer, int bmode) {
;     ...
;           float* xb;
;           const float* gv;
;           const float* xs;
;           if (trow == 0) {
;             xb = (float*)(ws + O_XC) + ((size_t)bb * CTXL + R) * D + col;
;             xs = (layer == 0) ? p.ctx + ((size_t)bb * CTXL + R) * D + col : xb;
;             gv = (const float*)(ws + O_MOD) + ((size_t)layer * 5 + 4) * 6144 + 4096 + col;
;           } else {
;             xb = p.out + ((size_t)bb * SEQ + (trow - CTXL) + R) * D + col;
;             xs = (layer == 0) ? p.x + ((size_t)bb * SEQ + (trow - CTXL) + R) * D + col : xb;
;             gv = (const float*)(ws + O_MOD) + ((size_t)layer * 5 + bb) * 6144 + 4096 + col;
;           }
.Lg5_half:
	s_mov_b64 s[4:5], 0x20000
	s_and_b64 vcc, exec, s[54:55]
	s_cbranch_vccz .Lg5h_ctx
	v_lshl_add_u64 v[52:53], v[40:41], 0, v[20:21]
	v_mov_b32_e32 v54, v42
	v_mov_b32_e32 v55, v43
	s_mov_b64 s[2:3], s[58:59]
	s_branch .Lg5h_common

; DEVI void gemm256(const P& p, const u16* A, int lda, const u16* Bt, int ldb, int K, int brow, int bcol, int mode,
;                         int aux, int layer, int bmode) {
;     ...
;     for (int it = 0; it < 16; ++it) {
;       const int R = it * 16 + (tid >> 5), c = tid & 31;
;       if ((c < 16) ? tr0 : tr1) continue;
;       const int row = brow + R, col = bcol + c * 8;
;       bf16x8 raw = *(const bf16x8*)(stg + R * 256 + SWZ(R, c) * 8);
;     ...
;         } else {
;           float* xb;
;           const float* gv;
;           const float* xs;
;           if (trow == 0) {
;             xb = (float*)(ws + O_XC) + ((size_t)bb * CTXL + R) * D + col;
;             xs = (layer == 0) ? p.ctx + ((size_t)bb * CTXL + R) * D + col : xb;
;             gv = (const float*)(ws + O_MOD) + ((size_t)layer * 5 + 4) * 6144 + 4096 + col;
;           } else {
;             xb = p.out + ((size_t)bb * SEQ + (trow - CTXL) + R) * D + col;
;             xs = (layer == 0) ? p.x + ((size_t)bb * SEQ + (trow - CTXL) + R) * D + col : xb;
;             gv = (const float*)(ws + O_MOD) + ((size_t)layer * 5 + bb) * 6144 + 4096 + col;
;           }
;           f32x4 x0 = *(const f32x4*)xs, x1 = *(const f32x4*)(xs + 4);
;           f32x4 g0 = *(const f32x4*)gv, g1 = *(const f32x4*)(gv + 4);
; #pragma unroll
;           for (int e = 0; e < 4; ++e) { x0[e] += PROBE_US * g0[e] * v[e]; x1[e] += PROBE_US * g1[e] * v[4 + e]; }
;           *(f32x4*)xb = x0;
;           *(f32x4*)(xb + 4) = x1;
.Lg5h_common:
	v_lshl_add_u64 v[56:57], s[2:3], 0, v[20:21]
	v_cndmask_b32_e64 v53, v55, v53, s[42:43]
	v_cndmask_b32_e64 v52, v54, v52, s[42:43]
	v_add_u32_e32 v168, 0x10000, v0
	global_load_dwordx4 v[44:47], v[56:57], off
	global_load_dwordx4 v[48:51], v[56:57], off offset:16
	global_load_dwordx4 v[66:69], v[52:53], off
	global_load_dwordx4 v[70:73], v[52:53], off offset:16
	v_lshl_add_u64 v[52:53], v[52:53], 0, s[4:5]
	global_load_dwordx4 v[74:77], v[52:53], off
	global_load_dwordx4 v[78:81], v[52:53], off offset:16
	v_lshl_add_u64 v[52:53], v[52:53], 0, s[4:5]
	global_load_dwordx4 v[82:85], v[52:53], off
	global_load_dwordx4 v[86:89], v[52:53], off offset:16
	v_lshl_add_u64 v[52:53], v[52:53], 0, s[4:5]
	global_load_dwordx4 v[90:93], v[52:53], off
	global_load_dwordx4 v[94:97], v[52:53], off offset:16
	v_lshl_add_u64 v[52:53], v[52:53], 0, s[4:5]
	global_load_dwordx4 v[98:101], v[52:53], off
	global_load_dwordx4 v[102:105], v[52:53], off offset:16
	v_lshl_add_u64 v[52:53], v[52:53], 0, s[4:5]
	global_load_dwordx4 v[106:109], v[52:53], off
	global_load_dwordx4 v[110:113], v[52:53], off offset:16
	v_lshl_add_u64 v[52:53], v[52:53], 0, s[4:5]
	global_load_dwordx4 v[114:117], v[52:53], off
	global_load_dwordx4 v[118:121], v[52:53], off offset:16
	v_lshl_add_u64 v[52:53], v[52:53], 0, s[4:5]
	global_load_dwordx4 v[122:125], v[52:53], off
	global_load_dwordx4 v[126:129], v[52:53], off offset:16
	ds_read_b128 v[136:139], v0
	ds_read_b128 v[140:143], v0 offset:8192
	ds_read_b128 v[144:147], v0 offset:16384
	ds_read_b128 v[148:151], v0 offset:24576
	ds_read_b128 v[152:155], v0 offset:32768
	ds_read_b128 v[156:159], v0 offset:40960
	ds_read_b128 v[160:163], v0 offset:49152
	ds_read_b128 v[164:167], v0 offset:57344
	s_waitcnt vmcnt(14) lgkmcnt(7)
	v_lshlrev_b32_e32 v56, 16, v136
	v_and_b32_e32 v57, 0xffff0000, v136
	v_lshlrev_b32_e32 v58, 16, v137
	v_and_b32_e32 v59, 0xffff0000, v137
	v_lshlrev_b32_e32 v60, 16, v138
	v_and_b32_e32 v61, 0xffff0000, v138
	v_lshlrev_b32_e32 v62, 16, v139
	v_and_b32_e32 v63, 0xffff0000, v139
	v_pk_fma_f32 v[66:67], v[44:45], v[56:57], v[66:67]
	v_pk_fma_f32 v[68:69], v[46:47], v[58:59], v[68:69]
	v_pk_fma_f32 v[70:71], v[48:49], v[60:61], v[70:71]
	v_pk_fma_f32 v[72:73], v[50:51], v[62:63], v[72:73]
	global_store_dwordx4 v[54:55], v[66:69], off
	global_store_dwordx4 v[54:55], v[70:73], off offset:16
	v_lshl_add_u64 v[54:55], v[54:55], 0, s[4:5]
	s_waitcnt vmcnt(14) lgkmcnt(6)
	v_lshlrev_b32_e32 v56, 16, v140
	v_and_b32_e32 v57, 0xffff0000, v140
	v_lshlrev_b32_e32 v58, 16, v141
	v_and_b32_e32 v59, 0xffff0000, v141
	v_lshlrev_b32_e32 v60, 16, v142
	v_and_b32_e32 v61, 0xffff0000, v142
	v_lshlrev_b32_e32 v62, 16, v143
	v_and_b32_e32 v63, 0xffff0000, v143
	v_pk_fma_f32 v[74:75], v[44:45], v[56:57], v[74:75]
	v_pk_fma_f32 v[76:77], v[46:47], v[58:59], v[76:77]
	v_pk_fma_f32 v[78:79], v[48:49], v[60:61], v[78:79]
	v_pk_fma_f32 v[80:81], v[50:51], v[62:63], v[80:81]
	global_store_dwordx4 v[54:55], v[74:77], off
	global_store_dwordx4 v[54:55], v[78:81], off offset:16
	v_lshl_add_u64 v[54:55], v[54:55], 0, s[4:5]
	s_waitcnt vmcnt(14) lgkmcnt(5)
	v_lshlrev_b32_e32 v56, 16, v144
	v_and_b32_e32 v57, 0xffff0000, v144
	v_lshlrev_b32_e32 v58, 16, v145
	v_and_b32_e32 v59, 0xffff0000, v145
	v_lshlrev_b32_e32 v60, 16, v146
	v_and_b32_e32 v61, 0xffff0000, v146
	v_lshlrev_b32_e32 v62, 16, v147
	v_and_b32_e32 v63, 0xffff0000, v147
	v_pk_fma_f32 v[82:83], v[44:45], v[56:57], v[82:83]
	v_pk_fma_f32 v[84:85], v[46:47], v[58:59], v[84:85]
	v_pk_fma_f32 v[86:87], v[48:49], v[60:61], v[86:87]
	v_pk_fma_f32 v[88:89], v[50:51], v[62:63], v[88:89]
	global_store_dwordx4 v[54:55], v[82:85], off
	global_store_dwordx4 v[54:55], v[86:89], off offset:16
	v_lshl_add_u64 v[54:55], v[54:55], 0, s[4:5]
	s_waitcnt vmcnt(14) lgkmcnt(4)
; DEVI void gemm256(const P& p, const u16* A, int lda, const u16* Bt, int ldb, int K, int brow, int bcol, int mode,
;                         int aux, int layer, int bmode) {
;     ...
;           f32x4 x0 = *(const f32x4*)xs, x1 = *(const f32x4*)(xs + 4);
;           f32x4 g0 = *(const f32x4*)gv, g1 = *(const f32x4*)(gv + 4);
; #pragma unroll
;           for (int e = 0; e < 4; ++e) { x0[e] += PROBE_US * g0[e] * v[e]; x1[e] += PROBE_US * g1[e] * v[4 + e]; }
;           *(f32x4*)xb = x0;
;           *(f32x4*)(xb + 4) = x1;
	v_lshlrev_b32_e32 v56, 16, v148
	v_and_b32_e32 v57, 0xffff0000, v148
	v_lshlrev_b32_e32 v58, 16, v149
	v_and_b32_e32 v59, 0xffff0000, v149
	v_lshlrev_b32_e32 v60, 16, v150
	v_and_b32_e32 v61, 0xffff0000, v150
	v_lshlrev_b32_e32 v62, 16, v151
	v_and_b32_e32 v63, 0xffff0000, v151
	v_pk_fma_f32 v[90:91], v[44:45], v[56:57], v[90:91]
	v_pk_fma_f32 v[92:93], v[46:47], v[58:59], v[92:93]
	v_pk_fma_f32 v[94:95], v[48:49], v[60:61], v[94:95]
	v_pk_fma_f32 v[96:97], v[50:51], v[62:63], v[96:97]
	global_store_dwordx4 v[54:55], v[90:93], off
	global_store_dwordx4 v[54:55], v[94:97], off offset:16
	v_lshl_add_u64 v[54:55], v[54:55], 0, s[4:5]
	s_waitcnt vmcnt(14) lgkmcnt(3)
	v_lshlrev_b32_e32 v56, 16, v152
	v_and_b32_e32 v57, 0xffff0000, v152
	v_lshlrev_b32_e32 v58, 16, v153
	v_and_b32_e32 v59, 0xffff0000, v153
	v_lshlrev_b32_e32 v60, 16, v154
	v_and_b32_e32 v61, 0xffff0000, v154
	v_lshlrev_b32_e32 v62, 16, v155
	v_and_b32_e32 v63, 0xffff0000, v155
	v_pk_fma_f32 v[98:99], v[44:45], v[56:57], v[98:99]
	v_pk_fma_f32 v[100:101], v[46:47], v[58:59], v[100:101]
	v_pk_fma_f32 v[102:103], v[48:49], v[60:61], v[102:103]
	v_pk_fma_f32 v[104:105], v[50:51], v[62:63], v[104:105]
	global_store_dwordx4 v[54:55], v[98:101], off
	global_store_dwordx4 v[54:55], v[102:105], off offset:16
	v_lshl_add_u64 v[54:55], v[54:55], 0, s[4:5]
	s_waitcnt vmcnt(14) lgkmcnt(2)
	v_lshlrev_b32_e32 v56, 16, v156
	v_and_b32_e32 v57, 0xffff0000, v156
	v_lshlrev_b32_e32 v58, 16, v157
	v_and_b32_e32 v59, 0xffff0000, v157
	v_lshlrev_b32_e32 v60, 16, v158
	v_and_b32_e32 v61, 0xffff0000, v158
	v_lshlrev_b32_e32 v62, 16, v159
	v_and_b32_e32 v63, 0xffff0000, v159
	v_pk_fma_f32 v[106:107], v[44:45], v[56:57], v[106:107]
	v_pk_fma_f32 v[108:109], v[46:47], v[58:59], v[108:109]
	v_pk_fma_f32 v[110:111], v[48:49], v[60:61], v[110:111]
	v_pk_fma_f32 v[112:113], v[50:51], v[62:63], v[112:113]
	global_store_dwordx4 v[54:55], v[106:109], off
	global_store_dwordx4 v[54:55], v[110:113], off offset:16
	v_lshl_add_u64 v[54:55], v[54:55], 0, s[4:5]
	s_waitcnt vmcnt(14) lgkmcnt(1)
	v_lshlrev_b32_e32 v56, 16, v160
	v_and_b32_e32 v57, 0xffff0000, v160
	v_lshlrev_b32_e32 v58, 16, v161
	v_and_b32_e32 v59, 0xffff0000, v161
	v_lshlrev_b32_e32 v60, 16, v162
	v_and_b32_e32 v61, 0xffff0000, v162
	v_lshlrev_b32_e32 v62, 16, v163
	v_and_b32_e32 v63, 0xffff0000, v163
	v_pk_fma_f32 v[114:115], v[44:45], v[56:57], v[114:115]
	v_pk_fma_f32 v[116:117], v[46:47], v[58:59], v[116:117]
	v_pk_fma_f32 v[118:119], v[48:49], v[60:61], v[118:119]
	v_pk_fma_f32 v[120:121], v[50:51], v[62:63], v[120:121]
	global_store_dwordx4 v[54:55], v[114:117], off
	global_store_dwordx4 v[54:55], v[118:121], off offset:16
	v_lshl_add_u64 v[54:55], v[54:55], 0, s[4:5]
	s_waitcnt vmcnt(14) lgkmcnt(0)
	v_lshlrev_b32_e32 v56, 16, v164
	v_and_b32_e32 v57, 0xffff0000, v164
	v_lshlrev_b32_e32 v58, 16, v165
	v_and_b32_e32 v59, 0xffff0000, v165
	v_lshlrev_b32_e32 v60, 16, v166
	v_and_b32_e32 v61, 0xffff0000, v166
	v_lshlrev_b32_e32 v62, 16, v167
	v_and_b32_e32 v63, 0xffff0000, v167
	v_pk_fma_f32 v[122:123], v[44:45], v[56:57], v[122:123]
	v_pk_fma_f32 v[124:125], v[46:47], v[58:59], v[124:125]
	v_pk_fma_f32 v[126:127], v[48:49], v[60:61], v[126:127]
	v_pk_fma_f32 v[128:129], v[50:51], v[62:63], v[128:129]
	global_store_dwordx4 v[54:55], v[122:125], off
	global_store_dwordx4 v[54:55], v[126:129], off offset:16
	v_lshl_add_u64 v[54:55], v[54:55], 0, s[4:5]
	s_branch .LBB0_305

; __global__ void __launch_bounds__(NTHR) mega(P p) {
;     ...
;         else if (step == 7 && l < 3) {
;           wl = l + 1; wmode = (nb == 256) ? 1 : 4;
;           if (nb == 256) {
;             count = 128; mod = 5;
;             if ((bid & 7) >= 4) { rank = (bid >> 3) * 4 + (bid & 7) - 4; lo = 4; width = 1; }
;             else wl = -1;
;           }
;         } else if (step == 8 && l < 3 && nb == 256 && (bid & 7) != 0) {
;           wl = l + 1; wmode = 1; rank = (bid >> 3) * 7 + (bid & 7) - 1; count = 224; mod = 5; lo = 0; width = 4;
;         }
;       }
;       if (wl >= 0 && (PHM & 2)) phase_wprep(p, wl, wmode, rank, count, mod, lo, width, sub_lo, sub_hi);
.LBB0_319:
	v_readlane_b32 s2, v249, 56
	s_cmp_eq_u32 s2, 3
	v_readlane_b32 s68, v249, 42
	s_mov_b64 s[0:1], -1
	s_cselect_b64 s[28:29], -1, 0
	s_and_b64 vcc, exec, s[50:51]
	v_readlane_b32 s69, v249, 43
	v_readlane_b32 s70, v249, 44
	v_readlane_b32 s71, v249, 45
	v_readlane_b32 s72, v249, 46
	v_readlane_b32 s73, v249, 47
	v_readlane_b32 s74, v249, 48
	v_readlane_b32 s75, v249, 49
	s_cbranch_vccz .LBB0_325
	v_readlane_b32 s0, v249, 56
	s_cmp_eq_u32 s0, 6
	s_cselect_b64 s[0:1], -1, 0
	s_or_b64 s[0:1], s[28:29], s[0:1]
	s_or_b64 s[2:3], s[38:39], s[0:1]
	s_cmp_lt_u32 s77, 54
	s_cselect_b64 s[0:1], -1, 0
	v_readlane_b32 s4, v251, 29
	s_and_b64 s[2:3], s[2:3], s[0:1]
	v_readlane_b32 s5, v251, 30
	s_and_b64 s[2:3], s[4:5], s[2:3]
	s_andn2_b64 vcc, exec, s[2:3]
	s_mov_b64 s[2:3], -1
	s_cbranch_vccz .LBB0_337
	v_readlane_b32 s2, v249, 56
	s_cmp_eq_u32 s2, 7
	s_cselect_b64 s[2:3], -1, 0
	s_and_b64 s[2:3], s[2:3], s[0:1]
	s_andn2_b64 vcc, exec, s[2:3]
	s_mov_b64 s[2:3], -1
	s_cbranch_vccz .LBB0_328
	v_readlane_b32 s2, v249, 56
	s_cmp_eq_u32 s2, 8
	s_cselect_b64 s[2:3], -1, 0
	s_and_b64 s[0:1], s[2:3], s[0:1]
	v_readlane_b32 s2, v251, 29
	v_readlane_b32 s3, v251, 30
	s_and_b64 s[0:1], s[2:3], s[0:1]
	s_andn2_b64 vcc, exec, s[0:1]
	s_mov_b32 s95, 1
	s_cbranch_vccnz .LBB0_327
	v_readlane_b32 s0, v251, 31
	v_readlane_b32 s1, v251, 32
	s_andn2_b64 vcc, exec, s[0:1]
	s_cbranch_vccnz .LBB0_333
	v_readlane_b32 s0, v249, 55
	s_mov_b32 s7, 1
	s_add_i32 s12, s0, 1
	s_movk_i32 s4, 0xc0
	s_mov_b32 s6, 5
	s_mov_b32 s95, 4
	v_readlane_b32 s5, v251, 33
	s_mov_b32 s9, 0
	s_cbranch_execz .LBB0_329
	s_branch .LBB0_336
